# out-proj and ff2 tile epilogues: batched read-modify-write instead of one load-wait-store round trip per element
# speedup vs baseline: 1.1472x; 1.0549x over previous
; DI int crow(int reg, int h) { return (reg & 3) + 8 * (reg >> 2) + 4 * h; }
; #define XCD_TILE_LOOP(MT, NTN, m_, n_) for (int lt_ = (bid >> 3), m_ = 0, n_ = 0; (lt_ < ((MT) >> 3) * (NTN)) && ((m_ = (bid & 7) + 8 * (lt_ / (NTN))), (n_ = lt_ % (NTN)), true); lt_ += (G >> 3))
; template <class Epi, class ColV>
; DI void gemm_tile(const bf16_t* __restrict__ A, int lda, const bf16_t* __restrict__ Bt, int ldb, int K, int m0, int n0, unsigned char* smem, Epi epi, ColV colv, const bf16_t* __restrict__ HYT = nullptr) {
;     ...
;     const float cv0 = colv(m0, n0 + 64 * wc + li), cv1 = colv(m0, n0 + 64 * wc + 32 + li);
; #pragma unroll
;     for (int mi = 0; mi < 2; ++mi)
; #pragma unroll
;         for (int ni = 0; ni < 2; ++ni)
; #pragma unroll
;             for (int reg = 0; reg < 16; ++reg)
;                 epi(m0 + 64 * wr + 32 * mi + crow(reg, lh), n0 + 64 * wc + 32 * ni + li, acc[mi][ni][reg], ni ? cv1 : cv0);
;     ...
;     case 11: {
;         float* out = p.out; float* XC = (float*)(p.ws + WS_XC);
;         auto gate = [&](int m0_, int c) { return MOD[(m0_ < NL ? (m0_ >> 12) : 4) * 6144 + 5120 + c]; };
;         auto epi = [&](int r, int c, float v, float ga) {
;             if (r < NL) out[(size_t)r * 1024 + c] += ga * v;
;             else XC[(size_t)(r - NL) * 1024 + c] += ga * v; };
;         XCD_TILE_LOOP(NL / 128, 8, tm, tn) gemm_tile((const bf16_t*)(p.ws + WS_HID), 4096, (const bf16_t*)(p.ws + wbase(layer) + W_FF2), 4096, 4096, tm * 128, tn * 128, smem, epi, gate);
.LBB0_37:
	s_ashr_i32 s12, s39, 12
	s_mulk_i32 s12, 0x1800
	s_add_i32 s13, s12, 0x1400
	v_or_b32_e32 v68, s40, v166
	v_or_b32_e32 v0, s13, v148
	v_add_u32_e32 v0, v0, v68
	v_readlane_b32 s18, v255, 30
	v_ashrrev_i32_e32 v1, 31, v0
	v_readlane_b32 s19, v255, 31
	s_addk_i32 s12, 0x1420
	v_mov_b32_e32 v82, s97
	v_lshl_add_u64 v[0:1], v[0:1], 2, s[18:19]
	global_load_dword v80, v[0:1], off
	v_or_b32_e32 v0, s12, v148
	v_add_u32_e32 v0, v0, v68
	v_ashrrev_i32_e32 v1, 31, v0
	v_lshl_add_u64 v[0:1], v[0:1], 2, s[18:19]
	global_load_dword v2, v[0:1], off
	v_add_u32_e32 v0, s38, v167
	v_lshl_or_b32 v81, v151, 2, v0
	v_or_b32_e32 v0, v68, v148
	v_lshlrev_b32_e32 v81, 12, v81
	v_lshl_add_u32 v81, v0, 2, v81
	v_mov_b32_e32 v0, v81
	global_load_dword v84, v0, s[24:25]
	global_load_dword v85, v0, s[24:25] offset:128
	v_add_u32_e32 v0, 0x1000, v0
	global_load_dword v86, v0, s[24:25]
	global_load_dword v87, v0, s[24:25] offset:128
	v_add_u32_e32 v0, 0x1000, v0
	global_load_dword v88, v0, s[24:25]
	global_load_dword v89, v0, s[24:25] offset:128
	v_add_u32_e32 v0, 0x1000, v0
	global_load_dword v90, v0, s[24:25]
	global_load_dword v91, v0, s[24:25] offset:128
	v_add_u32_e32 v0, 0x5000, v0
	global_load_dword v92, v0, s[24:25]
	global_load_dword v93, v0, s[24:25] offset:128
	v_add_u32_e32 v0, 0x1000, v0
	global_load_dword v94, v0, s[24:25]
	global_load_dword v95, v0, s[24:25] offset:128
	v_add_u32_e32 v0, 0x1000, v0
	global_load_dword v96, v0, s[24:25]
	global_load_dword v97, v0, s[24:25] offset:128
	v_add_u32_e32 v0, 0x1000, v0
	global_load_dword v98, v0, s[24:25]
	global_load_dword v99, v0, s[24:25] offset:128
	v_add_u32_e32 v0, 0x5000, v0
	global_load_dword v100, v0, s[24:25]
	global_load_dword v101, v0, s[24:25] offset:128
	v_add_u32_e32 v0, 0x1000, v0
	global_load_dword v102, v0, s[24:25]
	global_load_dword v103, v0, s[24:25] offset:128
	v_add_u32_e32 v0, 0x1000, v0
	global_load_dword v104, v0, s[24:25]
	global_load_dword v105, v0, s[24:25] offset:128
	v_add_u32_e32 v0, 0x1000, v0
	global_load_dword v106, v0, s[24:25]
	global_load_dword v107, v0, s[24:25] offset:128
	v_add_u32_e32 v0, 0x5000, v0
	global_load_dword v108, v0, s[24:25]
	global_load_dword v109, v0, s[24:25] offset:128
	v_add_u32_e32 v0, 0x1000, v0
	global_load_dword v110, v0, s[24:25]
	global_load_dword v111, v0, s[24:25] offset:128
	v_add_u32_e32 v0, 0x1000, v0
	global_load_dword v112, v0, s[24:25]
	global_load_dword v113, v0, s[24:25] offset:128
	v_add_u32_e32 v0, 0x1000, v0
	global_load_dword v114, v0, s[24:25]
	global_load_dword v115, v0, s[24:25] offset:128
	s_waitcnt vmcnt(0)
	v_fmac_f32_e32 v84, v52, v80
	v_fmac_f32_e32 v85, v36, v2
	v_fmac_f32_e32 v86, v53, v80
	v_fmac_f32_e32 v87, v37, v2
	v_fmac_f32_e32 v88, v54, v80
	v_fmac_f32_e32 v89, v38, v2
	v_fmac_f32_e32 v90, v55, v80
	v_fmac_f32_e32 v91, v39, v2
	v_fmac_f32_e32 v92, v56, v80
	v_fmac_f32_e32 v93, v40, v2
	v_fmac_f32_e32 v94, v57, v80
	v_fmac_f32_e32 v95, v41, v2
	v_fmac_f32_e32 v96, v58, v80
	v_fmac_f32_e32 v97, v42, v2
	v_fmac_f32_e32 v98, v59, v80
	v_fmac_f32_e32 v99, v43, v2
	v_fmac_f32_e32 v100, v60, v80
	v_fmac_f32_e32 v101, v44, v2
	v_fmac_f32_e32 v102, v61, v80
	v_fmac_f32_e32 v103, v45, v2
	v_fmac_f32_e32 v104, v62, v80
	v_fmac_f32_e32 v105, v46, v2
	v_fmac_f32_e32 v106, v63, v80
	v_fmac_f32_e32 v107, v47, v2
	v_fmac_f32_e32 v108, v64, v80
	v_fmac_f32_e32 v109, v48, v2
	v_fmac_f32_e32 v110, v65, v80
	v_fmac_f32_e32 v111, v49, v2
	v_fmac_f32_e32 v112, v66, v80
	v_fmac_f32_e32 v113, v50, v2
	v_fmac_f32_e32 v114, v67, v80
	v_fmac_f32_e32 v115, v51, v2
	v_mov_b32_e32 v0, v81
	global_store_dword v0, v84, s[24:25]
	global_store_dword v0, v85, s[24:25] offset:128
	v_add_u32_e32 v0, 0x1000, v0
	global_store_dword v0, v86, s[24:25]
	global_store_dword v0, v87, s[24:25] offset:128
	v_add_u32_e32 v0, 0x1000, v0
	global_store_dword v0, v88, s[24:25]
	global_store_dword v0, v89, s[24:25] offset:128
	v_add_u32_e32 v0, 0x1000, v0
	global_store_dword v0, v90, s[24:25]
	global_store_dword v0, v91, s[24:25] offset:128
	v_add_u32_e32 v0, 0x5000, v0
	global_store_dword v0, v92, s[24:25]
	global_store_dword v0, v93, s[24:25] offset:128
	v_add_u32_e32 v0, 0x1000, v0
	global_store_dword v0, v94, s[24:25]
	global_store_dword v0, v95, s[24:25] offset:128
	v_add_u32_e32 v0, 0x1000, v0
	global_store_dword v0, v96, s[24:25]
	global_store_dword v0, v97, s[24:25] offset:128
	v_add_u32_e32 v0, 0x1000, v0
	global_store_dword v0, v98, s[24:25]
	global_store_dword v0, v99, s[24:25] offset:128
	v_add_u32_e32 v0, 0x5000, v0
	global_store_dword v0, v100, s[24:25]
	global_store_dword v0, v101, s[24:25] offset:128
	v_add_u32_e32 v0, 0x1000, v0
	global_store_dword v0, v102, s[24:25]
	global_store_dword v0, v103, s[24:25] offset:128
	v_add_u32_e32 v0, 0x1000, v0
	global_store_dword v0, v104, s[24:25]
	global_store_dword v0, v105, s[24:25] offset:128
	v_add_u32_e32 v0, 0x1000, v0
	global_store_dword v0, v106, s[24:25]
	global_store_dword v0, v107, s[24:25] offset:128
	v_add_u32_e32 v0, 0x5000, v0
	global_store_dword v0, v108, s[24:25]
	global_store_dword v0, v109, s[24:25] offset:128
	v_add_u32_e32 v0, 0x1000, v0
	global_store_dword v0, v110, s[24:25]
; DI int crow(int reg, int h) { return (reg & 3) + 8 * (reg >> 2) + 4 * h; }
; #define XCD_TILE_LOOP(MT, NTN, m_, n_) for (int lt_ = (bid >> 3), m_ = 0, n_ = 0; (lt_ < ((MT) >> 3) * (NTN)) && ((m_ = (bid & 7) + 8 * (lt_ / (NTN))), (n_ = lt_ % (NTN)), true); lt_ += (G >> 3))
; template <class Epi, class ColV>
; DI void gemm_tile(const bf16_t* __restrict__ A, int lda, const bf16_t* __restrict__ Bt, int ldb, int K, int m0, int n0, unsigned char* smem, Epi epi, ColV colv, const bf16_t* __restrict__ HYT = nullptr) {
;     ...
;     const float cv0 = colv(m0, n0 + 64 * wc + li), cv1 = colv(m0, n0 + 64 * wc + 32 + li);
; #pragma unroll
;     for (int mi = 0; mi < 2; ++mi)
; #pragma unroll
;         for (int ni = 0; ni < 2; ++ni)
; #pragma unroll
;             for (int reg = 0; reg < 16; ++reg)
;                 epi(m0 + 64 * wr + 32 * mi + crow(reg, lh), n0 + 64 * wc + 32 * ni + li, acc[mi][ni][reg], ni ? cv1 : cv0);
;     ...
;     case 11: {
;         float* out = p.out; float* XC = (float*)(p.ws + WS_XC);
;         auto gate = [&](int m0_, int c) { return MOD[(m0_ < NL ? (m0_ >> 12) : 4) * 6144 + 5120 + c]; };
;         auto epi = [&](int r, int c, float v, float ga) {
;             if (r < NL) out[(size_t)r * 1024 + c] += ga * v;
;             else XC[(size_t)(r - NL) * 1024 + c] += ga * v; };
;         XCD_TILE_LOOP(NL / 128, 8, tm, tn) gemm_tile((const bf16_t*)(p.ws + WS_HID), 4096, (const bf16_t*)(p.ws + wbase(layer) + W_FF2), 4096, 4096, tm * 128, tn * 128, smem, epi, gate);
	global_store_dword v0, v111, s[24:25] offset:128
	v_add_u32_e32 v0, 0x1000, v0
	global_store_dword v0, v112, s[24:25]
	global_store_dword v0, v113, s[24:25] offset:128
	v_add_u32_e32 v0, 0x1000, v0
	global_store_dword v0, v114, s[24:25]
	global_store_dword v0, v115, s[24:25] offset:128
	v_add_u32_e32 v0, 0x20000, v81
	global_load_dword v116, v0, s[24:25]
	global_load_dword v117, v0, s[24:25] offset:128
	v_add_u32_e32 v0, 0x1000, v0
	global_load_dword v118, v0, s[24:25]
	global_load_dword v119, v0, s[24:25] offset:128
	v_add_u32_e32 v0, 0x1000, v0
	global_load_dword v120, v0, s[24:25]
	global_load_dword v121, v0, s[24:25] offset:128
	v_add_u32_e32 v0, 0x1000, v0
	global_load_dword v122, v0, s[24:25]
	global_load_dword v123, v0, s[24:25] offset:128
	v_add_u32_e32 v0, 0x5000, v0
	global_load_dword v124, v0, s[24:25]
	global_load_dword v125, v0, s[24:25] offset:128
	v_add_u32_e32 v0, 0x1000, v0
	global_load_dword v126, v0, s[24:25]
	global_load_dword v127, v0, s[24:25] offset:128
	v_add_u32_e32 v0, 0x1000, v0
	global_load_dword v128, v0, s[24:25]
	global_load_dword v129, v0, s[24:25] offset:128
	v_add_u32_e32 v0, 0x1000, v0
	global_load_dword v130, v0, s[24:25]
	global_load_dword v131, v0, s[24:25] offset:128
	v_add_u32_e32 v0, 0x5000, v0
	global_load_dword v132, v0, s[24:25]
	global_load_dword v133, v0, s[24:25] offset:128
	v_add_u32_e32 v0, 0x1000, v0
	global_load_dword v134, v0, s[24:25]
	global_load_dword v135, v0, s[24:25] offset:128
	v_add_u32_e32 v0, 0x1000, v0
	global_load_dword v136, v0, s[24:25]
	global_load_dword v137, v0, s[24:25] offset:128
	v_add_u32_e32 v0, 0x1000, v0
	global_load_dword v138, v0, s[24:25]
	global_load_dword v139, v0, s[24:25] offset:128
	v_add_u32_e32 v0, 0x5000, v0
	global_load_dword v140, v0, s[24:25]
	global_load_dword v141, v0, s[24:25] offset:128
	v_add_u32_e32 v0, 0x1000, v0
	global_load_dword v142, v0, s[24:25]
	global_load_dword v143, v0, s[24:25] offset:128
	v_add_u32_e32 v0, 0x1000, v0
	global_load_dword v144, v0, s[24:25]
	global_load_dword v145, v0, s[24:25] offset:128
	v_add_u32_e32 v0, 0x1000, v0
	global_load_dword v146, v0, s[24:25]
	global_load_dword v147, v0, s[24:25] offset:128
	s_waitcnt vmcnt(0)
	v_fmac_f32_e32 v116, v20, v80
	v_fmac_f32_e32 v117, v4, v2
	v_fmac_f32_e32 v118, v21, v80
	v_fmac_f32_e32 v119, v5, v2
	v_fmac_f32_e32 v120, v22, v80
	v_fmac_f32_e32 v121, v6, v2
	v_fmac_f32_e32 v122, v23, v80
	v_fmac_f32_e32 v123, v7, v2
	v_fmac_f32_e32 v124, v24, v80
	v_fmac_f32_e32 v125, v8, v2
	v_fmac_f32_e32 v126, v25, v80
	v_fmac_f32_e32 v127, v9, v2
	v_fmac_f32_e32 v128, v26, v80
	v_fmac_f32_e32 v129, v10, v2
	v_fmac_f32_e32 v130, v27, v80
	v_fmac_f32_e32 v131, v11, v2
	v_fmac_f32_e32 v132, v28, v80
	v_fmac_f32_e32 v133, v12, v2
	v_fmac_f32_e32 v134, v29, v80
	v_fmac_f32_e32 v135, v13, v2
	v_fmac_f32_e32 v136, v30, v80
	v_fmac_f32_e32 v137, v14, v2
	v_fmac_f32_e32 v138, v31, v80
	v_fmac_f32_e32 v139, v15, v2
	v_fmac_f32_e32 v140, v32, v80
	v_fmac_f32_e32 v141, v16, v2
	v_fmac_f32_e32 v142, v33, v80
	v_fmac_f32_e32 v143, v17, v2
	v_fmac_f32_e32 v144, v34, v80
	v_fmac_f32_e32 v145, v18, v2
	v_fmac_f32_e32 v146, v35, v80
	v_fmac_f32_e32 v147, v19, v2
	v_add_u32_e32 v0, 0x20000, v81
	global_store_dword v0, v116, s[24:25]
	global_store_dword v0, v117, s[24:25] offset:128
	v_add_u32_e32 v0, 0x1000, v0
	global_store_dword v0, v118, s[24:25]
	global_store_dword v0, v119, s[24:25] offset:128
	v_add_u32_e32 v0, 0x1000, v0
	global_store_dword v0, v120, s[24:25]
	global_store_dword v0, v121, s[24:25] offset:128
	v_add_u32_e32 v0, 0x1000, v0
	global_store_dword v0, v122, s[24:25]
	global_store_dword v0, v123, s[24:25] offset:128
	v_add_u32_e32 v0, 0x5000, v0
	global_store_dword v0, v124, s[24:25]
	global_store_dword v0, v125, s[24:25] offset:128
	v_add_u32_e32 v0, 0x1000, v0
	global_store_dword v0, v126, s[24:25]
	global_store_dword v0, v127, s[24:25] offset:128
	v_add_u32_e32 v0, 0x1000, v0
	global_store_dword v0, v128, s[24:25]
	global_store_dword v0, v129, s[24:25] offset:128
	v_add_u32_e32 v0, 0x1000, v0
	global_store_dword v0, v130, s[24:25]
	global_store_dword v0, v131, s[24:25] offset:128
	v_add_u32_e32 v0, 0x5000, v0
	global_store_dword v0, v132, s[24:25]
	global_store_dword v0, v133, s[24:25] offset:128
	v_add_u32_e32 v0, 0x1000, v0
	global_store_dword v0, v134, s[24:25]
	global_store_dword v0, v135, s[24:25] offset:128
	v_add_u32_e32 v0, 0x1000, v0
	global_store_dword v0, v136, s[24:25]
	global_store_dword v0, v137, s[24:25] offset:128
	v_add_u32_e32 v0, 0x1000, v0
	global_store_dword v0, v138, s[24:25]
	global_store_dword v0, v139, s[24:25] offset:128
	v_add_u32_e32 v0, 0x5000, v0
	global_store_dword v0, v140, s[24:25]
	global_store_dword v0, v141, s[24:25] offset:128
	v_add_u32_e32 v0, 0x1000, v0
	global_store_dword v0, v142, s[24:25]
	global_store_dword v0, v143, s[24:25] offset:128
	v_add_u32_e32 v0, 0x1000, v0
	global_store_dword v0, v144, s[24:25]
	global_store_dword v0, v145, s[24:25] offset:128
	v_add_u32_e32 v0, 0x1000, v0
	global_store_dword v0, v146, s[24:25]
	global_store_dword v0, v147, s[24:25] offset:128
	s_add_i32 s37, s37, s36
	s_cmpk_lt_i32 s37, 0x80
	s_cbranch_scc0 .LBB0_46

; template <class Epi, class ColV>
; DI void gemm_tile(const bf16_t* __restrict__ A, int lda, const bf16_t* __restrict__ Bt, int ldb, int K, int m0, int n0, unsigned char* smem, Epi epi, ColV colv, const bf16_t* __restrict__ HYT = nullptr) {
;     ...
;     auto gload = [&](u32x4 (&r)[8], int kt) {
; #pragma unroll
;         for (int i = 0; i < 4; ++i) { int id = tid + 256 * i, row = id >> 3, kc = id & 7;
;             if (HYT && kt >= 12) r[i] = *(const u32x4*)(HYT + (size_t)((kt - 12) * 64 + (id >> 4)) * NT + m0 + (id & 15) * 8);
;             else r[i] = *(const u32x4*)(A + (size_t)(m0 + row) * lda + kt * 64 + kc * 8);
;             r[4 + i] = *(const u32x4*)(Bt + (size_t)(n0 + row) * ldb + kt * 64 + kc * 8); }
;     };
;     auto sstore = [&](const u32x4 (&r)[8], int buf, int kt) {
; #pragma unroll
;         for (int i = 0; i < 4; ++i) { int id = tid + 256 * i, row = id >> 3, kc = id & 7;
;             if (HYT && kt >= 12) { const int kk = id >> 4, rr = (id & 15) * 8; bf16_t* d = As + (buf * 128 + rr) * LS + kk; const bf16x8 v = __builtin_bit_cast(bf16x8, r[i]);
; #pragma unroll
;                 for (int e = 0; e < 8; ++e) d[e * LS] = (bf16_t)v[e]; }
;             else *(u32x4*)(As + (buf * 128 + row) * LS + kc * 8) = r[i];
;             *(u32x4*)(Bs + (buf * 128 + row) * LS + kc * 8) = r[4 + i]; }
;     ...
;     gload(R0, 0); gload(R1, 1);
;     sstore(R0, 0, 0); __syncthreads();
.LBB0_79:
	s_ashr_i32 s12, s37, 31
	s_lshr_b32 s12, s12, 29
	s_add_i32 s12, s37, s12
	s_lshl_b32 s12, s12, 7
	s_and_b32 s38, s12, 0xfffffc00
	v_mov_b32_e32 v151, v168
	s_or_b32 s12, s38, s76
	s_ashr_i32 s13, s12, 31
	v_ashrrev_i32_e32 v38, 3, v151
	v_add_u32_e32 v0, s12, v38
	v_ashrrev_i32_e32 v1, 31, v0
	v_lshlrev_b64 v[0:1], 11, v[0:1]
	v_lshlrev_b32_e32 v2, 4, v151
	v_add_u32_e32 v40, 0x100, v151
	v_lshl_add_u64 v[0:1], s[94:95], 0, v[0:1]
	v_and_b32_e32 v2, 0x70, v2
	v_ashrrev_i32_e32 v41, 3, v40
	v_lshl_add_u64 v[160:161], v[0:1], 0, v[2:3]
	v_subrev_u32_e32 v0, s38, v38
	v_subrev_u32_e32 v16, s38, v41
	v_add_u32_e32 v42, 0x200, v151
	v_add_u32_e32 v0, s36, v0
	v_add_u32_e32 v12, s12, v41
	v_add_u32_e32 v16, s36, v16
	v_ashrrev_i32_e32 v43, 3, v42
	v_ashrrev_i32_e32 v1, 31, v0
	v_ashrrev_i32_e32 v13, 31, v12
	v_ashrrev_i32_e32 v17, 31, v16
	v_subrev_u32_e32 v24, s38, v43
	v_add_u32_e32 v44, 0x300, v151
	v_lshlrev_b64 v[0:1], 11, v[0:1]
	v_lshlrev_b64 v[12:13], 11, v[12:13]
	v_lshlrev_b64 v[16:17], 11, v[16:17]
	v_add_u32_e32 v20, s12, v43
	v_add_u32_e32 v24, s36, v24
	v_ashrrev_i32_e32 v45, 3, v44
	global_load_dwordx4 v[4:7], v[160:161], off
	v_lshl_add_u64 v[0:1], s[10:11], 0, v[0:1]
	v_lshl_add_u64 v[12:13], s[94:95], 0, v[12:13]
	v_lshl_add_u64 v[16:17], s[10:11], 0, v[16:17]
	v_ashrrev_i32_e32 v21, 31, v20
	v_ashrrev_i32_e32 v25, 31, v24
	v_subrev_u32_e32 v32, s38, v45
	v_lshl_add_u64 v[0:1], v[0:1], 0, v[2:3]
	v_lshl_add_u64 v[162:163], v[12:13], 0, v[2:3]
	v_lshl_add_u64 v[152:153], v[16:17], 0, v[2:3]
	v_lshlrev_b64 v[20:21], 11, v[20:21]
	v_lshlrev_b64 v[24:25], 11, v[24:25]
	v_add_u32_e32 v28, s12, v45
	v_add_u32_e32 v32, s36, v32
	global_load_dwordx4 v[8:11], v[0:1], off
	global_load_dwordx4 v[12:15], v[162:163], off
	global_load_dwordx4 v[16:19], v[152:153], off
	v_lshl_add_u64 v[20:21], s[94:95], 0, v[20:21]
	v_lshl_add_u64 v[24:25], s[10:11], 0, v[24:25]
	v_ashrrev_i32_e32 v29, 31, v28
	v_ashrrev_i32_e32 v33, 31, v32
	v_lshl_add_u64 v[164:165], v[20:21], 0, v[2:3]
	v_lshl_add_u64 v[154:155], v[24:25], 0, v[2:3]
	v_lshlrev_b64 v[28:29], 11, v[28:29]
	v_lshlrev_b64 v[32:33], 11, v[32:33]
	global_load_dwordx4 v[20:23], v[164:165], off
	global_load_dwordx4 v[24:27], v[154:155], off
	v_lshl_add_u64 v[28:29], s[94:95], 0, v[28:29]
	v_lshl_add_u64 v[32:33], s[10:11], 0, v[32:33]
	v_lshl_add_u64 v[166:167], v[28:29], 0, v[2:3]
	v_lshl_add_u64 v[156:157], v[32:33], 0, v[2:3]
	global_load_dwordx4 v[28:31], v[166:167], off
	global_load_dwordx4 v[32:35], v[156:157], off
	v_mul_lo_u32 v38, v38, s6
	v_add3_u32 v46, 0, v38, v2
	global_load_dwordx4 v[96:99], v[160:161], off offset:128
	global_load_dwordx4 v[92:95], v[0:1], off offset:128
	global_load_dwordx4 v[88:91], v[162:163], off offset:128
	global_load_dwordx4 v[84:87], v[152:153], off offset:128
	global_load_dwordx4 v[80:83], v[164:165], off offset:128
	global_load_dwordx4 v[76:79], v[154:155], off offset:128
	global_load_dwordx4 v[72:75], v[166:167], off offset:128
	global_load_dwordx4 v[68:71], v[156:157], off offset:128
	v_and_b32_e32 v37, 31, v151
	v_bfe_u32 v148, v151, 5, 1
	v_and_b32_e32 v36, 64, v151
	v_lshlrev_b32_e32 v39, 3, v151
	s_lshl_b64 s[40:41], s[12:13], 1
	s_add_u32 s40, s39, s40
	v_ashrrev_i32_e32 v202, 4, v151
	s_addc_u32 s41, s42, s41
	v_ashrrev_i32_e32 v205, 4, v40
	v_ashrrev_i32_e32 v204, 4, v42
	v_ashrrev_i32_e32 v203, 4, v44
	s_waitcnt vmcnt(15)
	ds_write_b128 v46, v[4:7]
	v_mul_lo_u32 v4, v41, s6
	v_add3_u32 v5, 0, v4, v2
	s_waitcnt vmcnt(14)
	ds_write_b128 v46, v[8:11] offset:36864
	s_waitcnt vmcnt(13)
	ds_write_b128 v5, v[12:15]
	s_waitcnt vmcnt(12)
	ds_write_b128 v5, v[16:19] offset:36864
	v_mul_lo_u32 v5, v43, s6
	v_add3_u32 v6, 0, v5, v2
	v_lshlrev_b32_e32 v8, 4, v148
	s_waitcnt vmcnt(11)
	ds_write_b128 v6, v[20:23]
	s_waitcnt vmcnt(10)
	ds_write_b128 v6, v[24:27] offset:36864
	v_mul_lo_u32 v6, v45, s6
	v_add3_u32 v7, 0, v6, v2
	s_waitcnt vmcnt(9)
	ds_write_b128 v7, v[28:31]
	s_waitcnt vmcnt(8)
	ds_write_b128 v7, v[32:35] offset:36864
	s_waitcnt lgkmcnt(0)
	s_barrier
	global_load_dwordx4 v[128:131], v[160:161], off offset:256
	global_load_dwordx4 v[124:127], v[0:1], off offset:256
	global_load_dwordx4 v[120:123], v[162:163], off offset:256
	global_load_dwordx4 v[116:119], v[152:153], off offset:256
	global_load_dwordx4 v[112:115], v[164:165], off offset:256
	global_load_dwordx4 v[108:111], v[154:155], off offset:256
	global_load_dwordx4 v[104:107], v[166:167], off offset:256
	global_load_dwordx4 v[100:103], v[156:157], off offset:256
	v_ashrrev_i32_e32 v7, 1, v151
	v_and_b32_e32 v190, 0xffffffc0, v7
	v_or_b32_e32 v7, v190, v37
	v_mul_lo_u32 v7, v7, s6
	v_add3_u32 v201, 0, v7, v8
	v_and_b32_e32 v7, 0x5f, v151
	v_mul_u32_u24_e32 v7, 0x90, v7
	v_add3_u32 v200, 0, v7, v8
	v_add_u32_e32 v7, 0, v2
	v_or_b32_e32 v2, 0x80, v37
	v_add_u32_e32 v9, v2, v190
	v_or_b32_e32 v2, v2, v36
	v_mul_lo_u32 v9, v9, s6
	v_mul_u32_u24_e32 v2, 0x90, v2
	v_add3_u32 v192, 0, v9, v8
	v_add3_u32 v191, 0, v2, v8
	v_and_b32_e32 v8, 0x78, v39
	v_lshlrev_b32_e32 v2, 1, v8
	v_mad_u32_u24 v8, v8, s6, 0
	v_lshl_add_u64 v[158:159], s[40:41], 0, v[2:3]
	v_add_u32_e32 v198, v7, v38
	v_lshl_add_u32 v199, v202, 1, v8
	v_add_u32_e32 v196, v7, v4
	v_lshl_add_u32 v197, v205, 1, v8
	v_add_u32_e32 v194, v7, v5
	v_lshl_add_u32 v195, v204, 1, v8
	v_add_u32_e32 v2, v7, v6
	v_lshl_add_u32 v193, v203, 1, v8
	ds_read_b128 v[4:7], v201 offset:4608
	ds_read_b128 v[8:11], v200 offset:41472
	ds_read_b128 v[12:15], v201
	ds_read_b128 v[132:135], v201 offset:32
	ds_read_b128 v[136:139], v201 offset:4640
	ds_read_b128 v[16:19], v200 offset:36864
	ds_read_b128 v[140:143], v200 offset:36896
	ds_read_b128 v[144:147], v200 offset:41504
	s_waitcnt lgkmcnt(2)
; #define MFMA(a, b, c) __builtin_amdgcn_mfma_f32_32x32x16_bf16((a), (b), (c), 0, 0, 0)
; template <class Epi, class ColV>
; DI void gemm_tile(const bf16_t* __restrict__ A, int lda, const bf16_t* __restrict__ Bt, int ldb, int K, int m0, int n0, unsigned char* smem, Epi epi, ColV colv, const bf16_t* __restrict__ HYT = nullptr) {
;     ...
;     auto step = [&](int kt, u32x4 (&ldset)[8], const u32x4 (&stset)[8]) {
;         const int buf = kt & 1;
;         if (kt + 2 < nk) gload(ldset, kt + 2);
;         const bf16_t* Ab = As + (buf * 128 + 64 * wr + li) * LS + 8 * lh;
;         const bf16_t* Bb = Bs + (buf * 128 + 64 * wc + li) * LS + 8 * lh;
;         bf16x8 fa[2][2], fb[2][2], ga[2][2], gb[2][2];
; #pragma unroll
;         for (int k2 = 0; k2 < 2; ++k2) { fa[k2][0] = ld8(Ab + 16 * k2); fa[k2][1] = ld8(Ab + 32 * LS + 16 * k2); fb[k2][0] = ld8(Bb + 16 * k2); fb[k2][1] = ld8(Bb + 32 * LS + 16 * k2); }
;         __builtin_amdgcn_sched_barrier(0);
; #pragma unroll
;         for (int k2 = 0; k2 < 2; ++k2) {
;             acc[0][0] = MFMA(fa[k2][0], fb[k2][0], acc[0][0]); acc[0][1] = MFMA(fa[k2][0], fb[k2][1], acc[0][1]);
;             acc[1][0] = MFMA(fa[k2][1], fb[k2][0], acc[1][0]); acc[1][1] = MFMA(fa[k2][1], fb[k2][1], acc[1][1]);
;         }
; #pragma unroll
;         for (int k2 = 0; k2 < 2; ++k2) { const int ks = 2 + k2; ga[k2][0] = ld8(Ab + 16 * ks); ga[k2][1] = ld8(Ab + 32 * LS + 16 * ks); gb[k2][0] = ld8(Bb + 16 * ks); gb[k2][1] = ld8(Bb + 32 * LS + 16 * ks); }
; #pragma unroll
;         for (int k2 = 0; k2 < 2; ++k2) {
;             acc[0][0] = MFMA(ga[k2][0], gb[k2][0], acc[0][0]); acc[0][1] = MFMA(ga[k2][0], gb[k2][1], acc[0][1]);
;             acc[1][0] = MFMA(ga[k2][1], gb[k2][0], acc[1][0]); acc[1][1] = MFMA(ga[k2][1], gb[k2][1], acc[1][1]);
;         }
;         if (kt + 1 < nk) sstore(stset, buf ^ 1, kt + 1);
; #pragma unroll
;         for (int i = 0; i < 8; ++i) { __builtin_amdgcn_sched_group_barrier(0x008, 1, 0); __builtin_amdgcn_sched_group_barrier(0x100, 1, 0); }
; #pragma unroll
;         for (int i = 0; i < 8; ++i) { __builtin_amdgcn_sched_group_barrier(0x008, 1, 0); __builtin_amdgcn_sched_group_barrier(0x200, 1, 0); }
;         __builtin_amdgcn_sched_barrier(0);
;         __syncthreads();
;     };
	v_mfma_f32_32x32x16_bf16 v[52:67], v[12:15], v[16:19], 0
	ds_read_b128 v[174:177], v201 offset:4704
	v_mfma_f32_32x32x16_bf16 v[36:51], v[12:15], v[8:11], 0
	ds_read_b128 v[178:181], v200 offset:36928
	v_mfma_f32_32x32x16_bf16 v[20:35], v[4:7], v[16:19], 0
	ds_read_b128 v[206:209], v200 offset:36960
	v_mfma_f32_32x32x16_bf16 v[4:19], v[4:7], v[8:11], 0
	ds_read_b128 v[210:213], v200 offset:41568
	s_waitcnt lgkmcnt(5)
	v_mfma_f32_32x32x16_bf16 v[52:67], v[132:135], v[140:143], v[52:67]
	s_waitcnt lgkmcnt(4)
	v_mfma_f32_32x32x16_bf16 v[36:51], v[132:135], v[144:147], v[36:51]
	v_mfma_f32_32x32x16_bf16 v[4:19], v[136:139], v[144:147], v[4:19]
	ds_read_b128 v[144:147], v201 offset:96
	ds_read_b128 v[132:135], v201 offset:4672
	v_mfma_f32_32x32x16_bf16 v[20:35], v[136:139], v[140:143], v[20:35]
	ds_read_b128 v[140:143], v201 offset:64
	ds_read_b128 v[136:139], v200 offset:41536
	s_waitcnt lgkmcnt(1)
	v_mfma_f32_32x32x16_bf16 v[52:67], v[140:143], v[178:181], v[52:67]
	s_waitcnt vmcnt(15)
	ds_write_b128 v198, v[96:99] offset:18432
	s_waitcnt lgkmcnt(1)
	v_mfma_f32_32x32x16_bf16 v[36:51], v[140:143], v[136:139], v[36:51]
	s_waitcnt vmcnt(14)
	ds_write_b128 v198, v[92:95] offset:55296
	v_mfma_f32_32x32x16_bf16 v[20:35], v[132:135], v[178:181], v[20:35]
	s_waitcnt vmcnt(13)
	ds_write_b128 v196, v[88:91] offset:18432
	v_mfma_f32_32x32x16_bf16 v[4:19], v[132:135], v[136:139], v[4:19]
	s_waitcnt vmcnt(12)
	ds_write_b128 v196, v[84:87] offset:55296
	v_mfma_f32_32x32x16_bf16 v[52:67], v[144:147], v[206:209], v[52:67]
	s_waitcnt vmcnt(11)
	ds_write_b128 v194, v[80:83] offset:18432
	v_mfma_f32_32x32x16_bf16 v[36:51], v[144:147], v[210:213], v[36:51]
	s_waitcnt vmcnt(10)
	ds_write_b128 v194, v[76:79] offset:55296
	v_mfma_f32_32x32x16_bf16 v[20:35], v[174:177], v[206:209], v[20:35]
	s_waitcnt vmcnt(9)
	ds_write_b128 v2, v[72:75] offset:18432
	v_mfma_f32_32x32x16_bf16 v[4:19], v[174:177], v[210:213], v[4:19]
	s_waitcnt vmcnt(8)
	ds_write_b128 v2, v[68:71] offset:55296
	s_waitcnt lgkmcnt(0)
	s_barrier
	global_load_dwordx4 v[144:147], v[160:161], off offset:384
	global_load_dwordx4 v[140:143], v[0:1], off offset:384
	global_load_dwordx4 v[136:139], v[162:163], off offset:384
	global_load_dwordx4 v[132:135], v[152:153], off offset:384
	global_load_dwordx4 v[92:95], v[164:165], off offset:384
	global_load_dwordx4 v[84:87], v[154:155], off offset:384
	global_load_dwordx4 v[76:79], v[166:167], off offset:384
	global_load_dwordx4 v[68:71], v[156:157], off offset:384
	ds_read_b128 v[72:75], v192
	ds_read_b128 v[80:83], v192 offset:32
	ds_read_b128 v[88:91], v192 offset:4608
	ds_read_b128 v[96:99], v192 offset:4640
	ds_read_b128 v[174:177], v191 offset:36864
	ds_read_b128 v[178:181], v191 offset:36896
	ds_read_b128 v[206:209], v191 offset:41472
	ds_read_b128 v[210:213], v191 offset:41504
	s_waitcnt lgkmcnt(3)
	v_mfma_f32_32x32x16_bf16 v[52:67], v[72:75], v[174:177], v[52:67]
	s_waitcnt lgkmcnt(1)
	v_mfma_f32_32x32x16_bf16 v[36:51], v[72:75], v[206:209], v[36:51]
	v_mfma_f32_32x32x16_bf16 v[4:19], v[88:91], v[206:209], v[4:19]
	s_waitcnt lgkmcnt(0)
	v_mfma_f32_32x32x16_bf16 v[36:51], v[80:83], v[210:213], v[36:51]
	v_mfma_f32_32x32x16_bf16 v[4:19], v[96:99], v[210:213], v[4:19]
	ds_read_b128 v[210:213], v191 offset:41568
	ds_read_b128 v[72:75], v192 offset:4672
	v_mfma_f32_32x32x16_bf16 v[20:35], v[88:91], v[174:177], v[20:35]
	ds_read_b128 v[174:177], v192 offset:4704
	ds_read_b128 v[88:91], v192 offset:64
	v_mfma_f32_32x32x16_bf16 v[52:67], v[80:83], v[178:181], v[52:67]
	ds_read_b128 v[206:209], v191 offset:36960
	ds_read_b128 v[80:83], v191 offset:41536
	v_mfma_f32_32x32x16_bf16 v[20:35], v[96:99], v[178:181], v[20:35]
	ds_read_b128 v[178:181], v191 offset:36928
	ds_read_b128 v[96:99], v192 offset:96
	s_waitcnt lgkmcnt(1)
	v_mfma_f32_32x32x16_bf16 v[52:67], v[88:91], v[178:181], v[52:67]
	s_waitcnt vmcnt(15)
	ds_write_b128 v198, v[128:131]
	v_mfma_f32_32x32x16_bf16 v[36:51], v[88:91], v[80:83], v[36:51]
	s_waitcnt vmcnt(14)
	ds_write_b128 v198, v[124:127] offset:36864
	v_mfma_f32_32x32x16_bf16 v[20:35], v[72:75], v[178:181], v[20:35]
	s_waitcnt vmcnt(13)
	ds_write_b128 v196, v[120:123]
	v_mfma_f32_32x32x16_bf16 v[4:19], v[72:75], v[80:83], v[4:19]
	s_waitcnt vmcnt(12)
	ds_write_b128 v196, v[116:119] offset:36864
	s_waitcnt lgkmcnt(4)
	v_mfma_f32_32x32x16_bf16 v[52:67], v[96:99], v[206:209], v[52:67]
	s_waitcnt vmcnt(11)
	ds_write_b128 v194, v[112:115]
	v_mfma_f32_32x32x16_bf16 v[36:51], v[96:99], v[210:213], v[36:51]
	s_waitcnt vmcnt(10)
	ds_write_b128 v194, v[108:111] offset:36864
	v_mfma_f32_32x32x16_bf16 v[20:35], v[174:177], v[206:209], v[20:35]
	s_waitcnt vmcnt(9)
	ds_write_b128 v2, v[104:107]
	v_mfma_f32_32x32x16_bf16 v[4:19], v[174:177], v[210:213], v[4:19]
	s_waitcnt vmcnt(8)
	ds_write_b128 v2, v[100:103] offset:36864
	s_waitcnt lgkmcnt(0)
	s_barrier
; #define MFMA(a, b, c) __builtin_amdgcn_mfma_f32_32x32x16_bf16((a), (b), (c), 0, 0, 0)
; template <class Epi, class ColV>
; DI void gemm_tile(const bf16_t* __restrict__ A, int lda, const bf16_t* __restrict__ Bt, int ldb, int K, int m0, int n0, unsigned char* smem, Epi epi, ColV colv, const bf16_t* __restrict__ HYT = nullptr) {
;     ...
;     auto step = [&](int kt, u32x4 (&ldset)[8], const u32x4 (&stset)[8]) {
;         const int buf = kt & 1;
;         if (kt + 2 < nk) gload(ldset, kt + 2);
;         const bf16_t* Ab = As + (buf * 128 + 64 * wr + li) * LS + 8 * lh;
;         const bf16_t* Bb = Bs + (buf * 128 + 64 * wc + li) * LS + 8 * lh;
;         bf16x8 fa[2][2], fb[2][2], ga[2][2], gb[2][2];
; #pragma unroll
;         for (int k2 = 0; k2 < 2; ++k2) { fa[k2][0] = ld8(Ab + 16 * k2); fa[k2][1] = ld8(Ab + 32 * LS + 16 * k2); fb[k2][0] = ld8(Bb + 16 * k2); fb[k2][1] = ld8(Bb + 32 * LS + 16 * k2); }
;         __builtin_amdgcn_sched_barrier(0);
; #pragma unroll
;         for (int k2 = 0; k2 < 2; ++k2) {
;             acc[0][0] = MFMA(fa[k2][0], fb[k2][0], acc[0][0]); acc[0][1] = MFMA(fa[k2][0], fb[k2][1], acc[0][1]);
;             acc[1][0] = MFMA(fa[k2][1], fb[k2][0], acc[1][0]); acc[1][1] = MFMA(fa[k2][1], fb[k2][1], acc[1][1]);
;         }
; #pragma unroll
;         for (int k2 = 0; k2 < 2; ++k2) { const int ks = 2 + k2; ga[k2][0] = ld8(Ab + 16 * ks); ga[k2][1] = ld8(Ab + 32 * LS + 16 * ks); gb[k2][0] = ld8(Bb + 16 * ks); gb[k2][1] = ld8(Bb + 32 * LS + 16 * ks); }
; #pragma unroll
;         for (int k2 = 0; k2 < 2; ++k2) {
;             acc[0][0] = MFMA(ga[k2][0], gb[k2][0], acc[0][0]); acc[0][1] = MFMA(ga[k2][0], gb[k2][1], acc[0][1]);
;             acc[1][0] = MFMA(ga[k2][1], gb[k2][0], acc[1][0]); acc[1][1] = MFMA(ga[k2][1], gb[k2][1], acc[1][1]);
;         }
;         if (kt + 1 < nk) sstore(stset, buf ^ 1, kt + 1);
; #pragma unroll
;         for (int i = 0; i < 8; ++i) { __builtin_amdgcn_sched_group_barrier(0x008, 1, 0); __builtin_amdgcn_sched_group_barrier(0x100, 1, 0); }
; #pragma unroll
;         for (int i = 0; i < 8; ++i) { __builtin_amdgcn_sched_group_barrier(0x008, 1, 0); __builtin_amdgcn_sched_group_barrier(0x200, 1, 0); }
;         __builtin_amdgcn_sched_barrier(0);
;         __syncthreads();
;     };
	global_load_dwordx4 v[124:127], v[160:161], off offset:512
	global_load_dwordx4 v[116:119], v[0:1], off offset:512
	global_load_dwordx4 v[108:111], v[162:163], off offset:512
	global_load_dwordx4 v[100:103], v[152:153], off offset:512
	global_load_dwordx4 v[96:99], v[164:165], off offset:512
	global_load_dwordx4 v[88:91], v[154:155], off offset:512
	global_load_dwordx4 v[80:83], v[166:167], off offset:512
	global_load_dwordx4 v[72:75], v[156:157], off offset:512
	ds_read_b128 v[104:107], v201
	ds_read_b128 v[112:115], v201 offset:32
	ds_read_b128 v[120:123], v201 offset:4608
	ds_read_b128 v[128:131], v201 offset:4640
	ds_read_b128 v[174:177], v200 offset:36864
	ds_read_b128 v[178:181], v200 offset:36896
	ds_read_b128 v[206:209], v200 offset:41472
	ds_read_b128 v[210:213], v200 offset:41504
	s_waitcnt lgkmcnt(3)
	v_mfma_f32_32x32x16_bf16 v[52:67], v[104:107], v[174:177], v[52:67]
	s_waitcnt lgkmcnt(1)
	v_mfma_f32_32x32x16_bf16 v[36:51], v[104:107], v[206:209], v[36:51]
	v_mfma_f32_32x32x16_bf16 v[4:19], v[120:123], v[206:209], v[4:19]
	s_waitcnt lgkmcnt(0)
	v_mfma_f32_32x32x16_bf16 v[36:51], v[112:115], v[210:213], v[36:51]
	v_mfma_f32_32x32x16_bf16 v[4:19], v[128:131], v[210:213], v[4:19]
	ds_read_b128 v[210:213], v200 offset:41568
	ds_read_b128 v[104:107], v201 offset:4672
	v_mfma_f32_32x32x16_bf16 v[20:35], v[120:123], v[174:177], v[20:35]
	ds_read_b128 v[174:177], v201 offset:4704
	ds_read_b128 v[120:123], v201 offset:64
	v_mfma_f32_32x32x16_bf16 v[52:67], v[112:115], v[178:181], v[52:67]
	ds_read_b128 v[206:209], v200 offset:36960
	ds_read_b128 v[112:115], v200 offset:41536
	v_mfma_f32_32x32x16_bf16 v[20:35], v[128:131], v[178:181], v[20:35]
	ds_read_b128 v[178:181], v200 offset:36928
	ds_read_b128 v[128:131], v201 offset:96
	s_waitcnt lgkmcnt(1)
	v_mfma_f32_32x32x16_bf16 v[52:67], v[120:123], v[178:181], v[52:67]
	s_waitcnt vmcnt(15)
	ds_write_b128 v198, v[144:147] offset:18432
	v_mfma_f32_32x32x16_bf16 v[36:51], v[120:123], v[112:115], v[36:51]
	s_waitcnt vmcnt(14)
	ds_write_b128 v198, v[140:143] offset:55296
	v_mfma_f32_32x32x16_bf16 v[20:35], v[104:107], v[178:181], v[20:35]
	s_waitcnt vmcnt(13)
	ds_write_b128 v196, v[136:139] offset:18432
	v_mfma_f32_32x32x16_bf16 v[4:19], v[104:107], v[112:115], v[4:19]
	s_waitcnt vmcnt(12)
	ds_write_b128 v196, v[132:135] offset:55296
	s_waitcnt lgkmcnt(4)
	v_mfma_f32_32x32x16_bf16 v[52:67], v[128:131], v[206:209], v[52:67]
	s_waitcnt vmcnt(11)
	ds_write_b128 v194, v[92:95] offset:18432
	v_mfma_f32_32x32x16_bf16 v[36:51], v[128:131], v[210:213], v[36:51]
	s_waitcnt vmcnt(10)
	ds_write_b128 v194, v[84:87] offset:55296
	v_mfma_f32_32x32x16_bf16 v[20:35], v[174:177], v[206:209], v[20:35]
	s_waitcnt vmcnt(9)
	ds_write_b128 v2, v[76:79] offset:18432
	v_mfma_f32_32x32x16_bf16 v[4:19], v[174:177], v[210:213], v[4:19]
	s_waitcnt vmcnt(8)
	ds_write_b128 v2, v[68:71] offset:55296
	s_waitcnt lgkmcnt(0)
	s_barrier
	global_load_dwordx4 v[128:131], v[160:161], off offset:640
	global_load_dwordx4 v[120:123], v[0:1], off offset:640
	global_load_dwordx4 v[112:115], v[162:163], off offset:640
	global_load_dwordx4 v[104:107], v[152:153], off offset:640
	global_load_dwordx4 v[92:95], v[164:165], off offset:640
	global_load_dwordx4 v[84:87], v[154:155], off offset:640
	global_load_dwordx4 v[76:79], v[166:167], off offset:640
	global_load_dwordx4 v[68:71], v[156:157], off offset:640
	ds_read_b128 v[132:135], v192
	ds_read_b128 v[136:139], v192 offset:32
	ds_read_b128 v[140:143], v192 offset:4608
	ds_read_b128 v[144:147], v192 offset:4640
	ds_read_b128 v[174:177], v191 offset:36864
	ds_read_b128 v[178:181], v191 offset:36896
	ds_read_b128 v[206:209], v191 offset:41472
	ds_read_b128 v[210:213], v191 offset:41504
	s_waitcnt lgkmcnt(3)
	v_mfma_f32_32x32x16_bf16 v[52:67], v[132:135], v[174:177], v[52:67]
	s_waitcnt lgkmcnt(1)
	v_mfma_f32_32x32x16_bf16 v[36:51], v[132:135], v[206:209], v[36:51]
	v_mfma_f32_32x32x16_bf16 v[4:19], v[140:143], v[206:209], v[4:19]
	s_waitcnt lgkmcnt(0)
	v_mfma_f32_32x32x16_bf16 v[36:51], v[136:139], v[210:213], v[36:51]
	v_mfma_f32_32x32x16_bf16 v[4:19], v[144:147], v[210:213], v[4:19]
	ds_read_b128 v[210:213], v191 offset:41568
	ds_read_b128 v[132:135], v192 offset:4672
	v_mfma_f32_32x32x16_bf16 v[20:35], v[140:143], v[174:177], v[20:35]
	ds_read_b128 v[174:177], v192 offset:4704
	ds_read_b128 v[140:143], v192 offset:64
	v_mfma_f32_32x32x16_bf16 v[52:67], v[136:139], v[178:181], v[52:67]
	ds_read_b128 v[206:209], v191 offset:36960
	ds_read_b128 v[136:139], v191 offset:41536
	v_mfma_f32_32x32x16_bf16 v[20:35], v[144:147], v[178:181], v[20:35]
	ds_read_b128 v[178:181], v191 offset:36928
	ds_read_b128 v[144:147], v192 offset:96
	s_waitcnt lgkmcnt(1)
	v_mfma_f32_32x32x16_bf16 v[52:67], v[140:143], v[178:181], v[52:67]
	s_waitcnt vmcnt(15)
	ds_write_b128 v198, v[124:127]
	v_mfma_f32_32x32x16_bf16 v[36:51], v[140:143], v[136:139], v[36:51]
	s_waitcnt vmcnt(14)
	ds_write_b128 v198, v[116:119] offset:36864
	v_mfma_f32_32x32x16_bf16 v[20:35], v[132:135], v[178:181], v[20:35]
	s_waitcnt vmcnt(13)
	ds_write_b128 v196, v[108:111]
	v_mfma_f32_32x32x16_bf16 v[4:19], v[132:135], v[136:139], v[4:19]
	s_waitcnt vmcnt(12)
	ds_write_b128 v196, v[100:103] offset:36864
	s_waitcnt lgkmcnt(4)
	v_mfma_f32_32x32x16_bf16 v[52:67], v[144:147], v[206:209], v[52:67]
	s_waitcnt vmcnt(11)
	ds_write_b128 v194, v[96:99]
	v_mfma_f32_32x32x16_bf16 v[36:51], v[144:147], v[210:213], v[36:51]
	s_waitcnt vmcnt(10)
	ds_write_b128 v194, v[88:91] offset:36864
	v_mfma_f32_32x32x16_bf16 v[20:35], v[174:177], v[206:209], v[20:35]
	s_waitcnt vmcnt(9)
	ds_write_b128 v2, v[80:83]
	v_mfma_f32_32x32x16_bf16 v[4:19], v[174:177], v[210:213], v[4:19]
	s_waitcnt vmcnt(8)
	ds_write_b128 v2, v[72:75] offset:36864
	s_waitcnt lgkmcnt(0)
	s_barrier
; #define MFMA(a, b, c) __builtin_amdgcn_mfma_f32_32x32x16_bf16((a), (b), (c), 0, 0, 0)
; template <class Epi, class ColV>
; DI void gemm_tile(const bf16_t* __restrict__ A, int lda, const bf16_t* __restrict__ Bt, int ldb, int K, int m0, int n0, unsigned char* smem, Epi epi, ColV colv, const bf16_t* __restrict__ HYT = nullptr) {
;     ...
;     auto step = [&](int kt, u32x4 (&ldset)[8], const u32x4 (&stset)[8]) {
;         const int buf = kt & 1;
;         if (kt + 2 < nk) gload(ldset, kt + 2);
;         const bf16_t* Ab = As + (buf * 128 + 64 * wr + li) * LS + 8 * lh;
;         const bf16_t* Bb = Bs + (buf * 128 + 64 * wc + li) * LS + 8 * lh;
;         bf16x8 fa[2][2], fb[2][2], ga[2][2], gb[2][2];
; #pragma unroll
;         for (int k2 = 0; k2 < 2; ++k2) { fa[k2][0] = ld8(Ab + 16 * k2); fa[k2][1] = ld8(Ab + 32 * LS + 16 * k2); fb[k2][0] = ld8(Bb + 16 * k2); fb[k2][1] = ld8(Bb + 32 * LS + 16 * k2); }
;         __builtin_amdgcn_sched_barrier(0);
; #pragma unroll
;         for (int k2 = 0; k2 < 2; ++k2) {
;             acc[0][0] = MFMA(fa[k2][0], fb[k2][0], acc[0][0]); acc[0][1] = MFMA(fa[k2][0], fb[k2][1], acc[0][1]);
;             acc[1][0] = MFMA(fa[k2][1], fb[k2][0], acc[1][0]); acc[1][1] = MFMA(fa[k2][1], fb[k2][1], acc[1][1]);
;         }
; #pragma unroll
;         for (int k2 = 0; k2 < 2; ++k2) { const int ks = 2 + k2; ga[k2][0] = ld8(Ab + 16 * ks); ga[k2][1] = ld8(Ab + 32 * LS + 16 * ks); gb[k2][0] = ld8(Bb + 16 * ks); gb[k2][1] = ld8(Bb + 32 * LS + 16 * ks); }
; #pragma unroll
;         for (int k2 = 0; k2 < 2; ++k2) {
;             acc[0][0] = MFMA(ga[k2][0], gb[k2][0], acc[0][0]); acc[0][1] = MFMA(ga[k2][0], gb[k2][1], acc[0][1]);
;             acc[1][0] = MFMA(ga[k2][1], gb[k2][0], acc[1][0]); acc[1][1] = MFMA(ga[k2][1], gb[k2][1], acc[1][1]);
;         }
;         if (kt + 1 < nk) sstore(stset, buf ^ 1, kt + 1);
; #pragma unroll
;         for (int i = 0; i < 8; ++i) { __builtin_amdgcn_sched_group_barrier(0x008, 1, 0); __builtin_amdgcn_sched_group_barrier(0x100, 1, 0); }
; #pragma unroll
;         for (int i = 0; i < 8; ++i) { __builtin_amdgcn_sched_group_barrier(0x008, 1, 0); __builtin_amdgcn_sched_group_barrier(0x200, 1, 0); }
;         __builtin_amdgcn_sched_barrier(0);
;         __syncthreads();
;     };
	global_load_dwordx4 v[124:127], v[160:161], off offset:768
	global_load_dwordx4 v[116:119], v[0:1], off offset:768
	global_load_dwordx4 v[108:111], v[162:163], off offset:768
	global_load_dwordx4 v[100:103], v[152:153], off offset:768
	global_load_dwordx4 v[96:99], v[164:165], off offset:768
	global_load_dwordx4 v[88:91], v[154:155], off offset:768
	global_load_dwordx4 v[80:83], v[166:167], off offset:768
	global_load_dwordx4 v[72:75], v[156:157], off offset:768
	ds_read_b128 v[132:135], v201
	ds_read_b128 v[136:139], v201 offset:32
	ds_read_b128 v[140:143], v201 offset:4608
	ds_read_b128 v[144:147], v201 offset:4640
	ds_read_b128 v[174:177], v200 offset:36864
	ds_read_b128 v[178:181], v200 offset:36896
	ds_read_b128 v[206:209], v200 offset:41472
	ds_read_b128 v[210:213], v200 offset:41504
	s_waitcnt lgkmcnt(3)
	v_mfma_f32_32x32x16_bf16 v[52:67], v[132:135], v[174:177], v[52:67]
	s_waitcnt lgkmcnt(1)
	v_mfma_f32_32x32x16_bf16 v[36:51], v[132:135], v[206:209], v[36:51]
	v_mfma_f32_32x32x16_bf16 v[4:19], v[140:143], v[206:209], v[4:19]
	s_waitcnt lgkmcnt(0)
	v_mfma_f32_32x32x16_bf16 v[36:51], v[136:139], v[210:213], v[36:51]
	v_mfma_f32_32x32x16_bf16 v[4:19], v[144:147], v[210:213], v[4:19]
	ds_read_b128 v[210:213], v200 offset:41568
	ds_read_b128 v[132:135], v201 offset:4672
	v_mfma_f32_32x32x16_bf16 v[20:35], v[140:143], v[174:177], v[20:35]
	ds_read_b128 v[174:177], v201 offset:4704
	ds_read_b128 v[140:143], v201 offset:64
	v_mfma_f32_32x32x16_bf16 v[52:67], v[136:139], v[178:181], v[52:67]
	ds_read_b128 v[206:209], v200 offset:36960
	ds_read_b128 v[136:139], v200 offset:41536
	v_mfma_f32_32x32x16_bf16 v[20:35], v[144:147], v[178:181], v[20:35]
	ds_read_b128 v[178:181], v200 offset:36928
	ds_read_b128 v[144:147], v201 offset:96
	s_waitcnt lgkmcnt(1)
	v_mfma_f32_32x32x16_bf16 v[52:67], v[140:143], v[178:181], v[52:67]
	s_waitcnt vmcnt(15)
	ds_write_b128 v198, v[128:131] offset:18432
	v_mfma_f32_32x32x16_bf16 v[36:51], v[140:143], v[136:139], v[36:51]
	s_waitcnt vmcnt(14)
	ds_write_b128 v198, v[120:123] offset:55296
	v_mfma_f32_32x32x16_bf16 v[20:35], v[132:135], v[178:181], v[20:35]
	s_waitcnt vmcnt(13)
	ds_write_b128 v196, v[112:115] offset:18432
	v_mfma_f32_32x32x16_bf16 v[4:19], v[132:135], v[136:139], v[4:19]
	s_waitcnt vmcnt(12)
	ds_write_b128 v196, v[104:107] offset:55296
	s_waitcnt lgkmcnt(4)
	v_mfma_f32_32x32x16_bf16 v[52:67], v[144:147], v[206:209], v[52:67]
	s_waitcnt vmcnt(11)
	ds_write_b128 v194, v[92:95] offset:18432
	v_mfma_f32_32x32x16_bf16 v[36:51], v[144:147], v[210:213], v[36:51]
	s_waitcnt vmcnt(10)
	ds_write_b128 v194, v[84:87] offset:55296
	v_mfma_f32_32x32x16_bf16 v[20:35], v[174:177], v[206:209], v[20:35]
	s_waitcnt vmcnt(9)
	ds_write_b128 v2, v[76:79] offset:18432
	v_mfma_f32_32x32x16_bf16 v[4:19], v[174:177], v[210:213], v[4:19]
	s_waitcnt vmcnt(8)
	ds_write_b128 v2, v[68:71] offset:55296
	s_waitcnt lgkmcnt(0)
	s_barrier
	global_load_dwordx4 v[128:131], v[160:161], off offset:896
	global_load_dwordx4 v[120:123], v[0:1], off offset:896
	global_load_dwordx4 v[112:115], v[162:163], off offset:896
	global_load_dwordx4 v[104:107], v[152:153], off offset:896
	global_load_dwordx4 v[92:95], v[164:165], off offset:896
	global_load_dwordx4 v[84:87], v[154:155], off offset:896
	global_load_dwordx4 v[76:79], v[166:167], off offset:896
	global_load_dwordx4 v[68:71], v[156:157], off offset:896
	ds_read_b128 v[132:135], v192
	ds_read_b128 v[136:139], v192 offset:32
	ds_read_b128 v[140:143], v192 offset:4608
	ds_read_b128 v[144:147], v192 offset:4640
	ds_read_b128 v[174:177], v191 offset:36864
	ds_read_b128 v[178:181], v191 offset:36896
	ds_read_b128 v[206:209], v191 offset:41472
	ds_read_b128 v[210:213], v191 offset:41504
	s_waitcnt lgkmcnt(3)
	v_mfma_f32_32x32x16_bf16 v[52:67], v[132:135], v[174:177], v[52:67]
	s_waitcnt lgkmcnt(1)
	v_mfma_f32_32x32x16_bf16 v[36:51], v[132:135], v[206:209], v[36:51]
	v_mfma_f32_32x32x16_bf16 v[4:19], v[140:143], v[206:209], v[4:19]
	s_waitcnt lgkmcnt(0)
	v_mfma_f32_32x32x16_bf16 v[36:51], v[136:139], v[210:213], v[36:51]
	v_mfma_f32_32x32x16_bf16 v[4:19], v[144:147], v[210:213], v[4:19]
	ds_read_b128 v[210:213], v191 offset:41568
	ds_read_b128 v[132:135], v192 offset:4672
	v_mfma_f32_32x32x16_bf16 v[20:35], v[140:143], v[174:177], v[20:35]
	ds_read_b128 v[174:177], v192 offset:4704
	ds_read_b128 v[140:143], v192 offset:64
	v_mfma_f32_32x32x16_bf16 v[52:67], v[136:139], v[178:181], v[52:67]
	ds_read_b128 v[206:209], v191 offset:36960
	ds_read_b128 v[136:139], v191 offset:41536
	v_mfma_f32_32x32x16_bf16 v[20:35], v[144:147], v[178:181], v[20:35]
	ds_read_b128 v[178:181], v191 offset:36928
	ds_read_b128 v[144:147], v192 offset:96
	s_waitcnt lgkmcnt(1)
	v_mfma_f32_32x32x16_bf16 v[52:67], v[140:143], v[178:181], v[52:67]
	s_waitcnt vmcnt(15)
	ds_write_b128 v198, v[124:127]
	v_mfma_f32_32x32x16_bf16 v[36:51], v[140:143], v[136:139], v[36:51]
	s_waitcnt vmcnt(14)
	ds_write_b128 v198, v[116:119] offset:36864
	v_mfma_f32_32x32x16_bf16 v[20:35], v[132:135], v[178:181], v[20:35]
	s_waitcnt vmcnt(13)
	ds_write_b128 v196, v[108:111]
	v_mfma_f32_32x32x16_bf16 v[4:19], v[132:135], v[136:139], v[4:19]
	s_waitcnt vmcnt(12)
	ds_write_b128 v196, v[100:103] offset:36864
	s_waitcnt lgkmcnt(4)
	v_mfma_f32_32x32x16_bf16 v[52:67], v[144:147], v[206:209], v[52:67]
	s_waitcnt vmcnt(11)
	ds_write_b128 v194, v[96:99]
	v_mfma_f32_32x32x16_bf16 v[36:51], v[144:147], v[210:213], v[36:51]
	s_waitcnt vmcnt(10)
	ds_write_b128 v194, v[88:91] offset:36864
	v_mfma_f32_32x32x16_bf16 v[20:35], v[174:177], v[206:209], v[20:35]
	s_waitcnt vmcnt(9)
	ds_write_b128 v2, v[80:83]
	v_mfma_f32_32x32x16_bf16 v[4:19], v[174:177], v[210:213], v[4:19]
	s_waitcnt vmcnt(8)
	ds_write_b128 v2, v[72:75] offset:36864
	s_waitcnt lgkmcnt(0)
	s_barrier
; #define MFMA(a, b, c) __builtin_amdgcn_mfma_f32_32x32x16_bf16((a), (b), (c), 0, 0, 0)
; template <class Epi, class ColV>
; DI void gemm_tile(const bf16_t* __restrict__ A, int lda, const bf16_t* __restrict__ Bt, int ldb, int K, int m0, int n0, unsigned char* smem, Epi epi, ColV colv, const bf16_t* __restrict__ HYT = nullptr) {
;     ...
;     auto step = [&](int kt, u32x4 (&ldset)[8], const u32x4 (&stset)[8]) {
;         const int buf = kt & 1;
;         if (kt + 2 < nk) gload(ldset, kt + 2);
;         const bf16_t* Ab = As + (buf * 128 + 64 * wr + li) * LS + 8 * lh;
;         const bf16_t* Bb = Bs + (buf * 128 + 64 * wc + li) * LS + 8 * lh;
;         bf16x8 fa[2][2], fb[2][2], ga[2][2], gb[2][2];
; #pragma unroll
;         for (int k2 = 0; k2 < 2; ++k2) { fa[k2][0] = ld8(Ab + 16 * k2); fa[k2][1] = ld8(Ab + 32 * LS + 16 * k2); fb[k2][0] = ld8(Bb + 16 * k2); fb[k2][1] = ld8(Bb + 32 * LS + 16 * k2); }
;         __builtin_amdgcn_sched_barrier(0);
; #pragma unroll
;         for (int k2 = 0; k2 < 2; ++k2) {
;             acc[0][0] = MFMA(fa[k2][0], fb[k2][0], acc[0][0]); acc[0][1] = MFMA(fa[k2][0], fb[k2][1], acc[0][1]);
;             acc[1][0] = MFMA(fa[k2][1], fb[k2][0], acc[1][0]); acc[1][1] = MFMA(fa[k2][1], fb[k2][1], acc[1][1]);
;         }
; #pragma unroll
;         for (int k2 = 0; k2 < 2; ++k2) { const int ks = 2 + k2; ga[k2][0] = ld8(Ab + 16 * ks); ga[k2][1] = ld8(Ab + 32 * LS + 16 * ks); gb[k2][0] = ld8(Bb + 16 * ks); gb[k2][1] = ld8(Bb + 32 * LS + 16 * ks); }
; #pragma unroll
;         for (int k2 = 0; k2 < 2; ++k2) {
;             acc[0][0] = MFMA(ga[k2][0], gb[k2][0], acc[0][0]); acc[0][1] = MFMA(ga[k2][0], gb[k2][1], acc[0][1]);
;             acc[1][0] = MFMA(ga[k2][1], gb[k2][0], acc[1][0]); acc[1][1] = MFMA(ga[k2][1], gb[k2][1], acc[1][1]);
;         }
;         if (kt + 1 < nk) sstore(stset, buf ^ 1, kt + 1);
; #pragma unroll
;         for (int i = 0; i < 8; ++i) { __builtin_amdgcn_sched_group_barrier(0x008, 1, 0); __builtin_amdgcn_sched_group_barrier(0x100, 1, 0); }
; #pragma unroll
;         for (int i = 0; i < 8; ++i) { __builtin_amdgcn_sched_group_barrier(0x008, 1, 0); __builtin_amdgcn_sched_group_barrier(0x200, 1, 0); }
;         __builtin_amdgcn_sched_barrier(0);
;         __syncthreads();
;     };
	global_load_dwordx4 v[132:135], v[160:161], off offset:1024
	global_load_dwordx4 v[124:127], v[0:1], off offset:1024
	global_load_dwordx4 v[108:111], v[162:163], off offset:1024
	global_load_dwordx4 v[100:103], v[152:153], off offset:1024
	global_load_dwordx4 v[96:99], v[164:165], off offset:1024
	global_load_dwordx4 v[88:91], v[154:155], off offset:1024
	global_load_dwordx4 v[80:83], v[166:167], off offset:1024
	global_load_dwordx4 v[72:75], v[156:157], off offset:1024
	ds_read_b128 v[116:119], v201
	ds_read_b128 v[136:139], v201 offset:32
	ds_read_b128 v[140:143], v201 offset:4608
	ds_read_b128 v[144:147], v201 offset:4640
	ds_read_b128 v[174:177], v200 offset:36864
	ds_read_b128 v[178:181], v200 offset:36896
	ds_read_b128 v[206:209], v200 offset:41472
	ds_read_b128 v[210:213], v200 offset:41504
	s_waitcnt lgkmcnt(3)
	v_mfma_f32_32x32x16_bf16 v[52:67], v[116:119], v[174:177], v[52:67]
	s_waitcnt lgkmcnt(1)
	v_mfma_f32_32x32x16_bf16 v[36:51], v[116:119], v[206:209], v[36:51]
	v_mfma_f32_32x32x16_bf16 v[4:19], v[140:143], v[206:209], v[4:19]
	s_waitcnt lgkmcnt(0)
	v_mfma_f32_32x32x16_bf16 v[36:51], v[136:139], v[210:213], v[36:51]
	v_mfma_f32_32x32x16_bf16 v[4:19], v[144:147], v[210:213], v[4:19]
	ds_read_b128 v[210:213], v200 offset:41568
	ds_read_b128 v[116:119], v201 offset:4672
	v_mfma_f32_32x32x16_bf16 v[20:35], v[140:143], v[174:177], v[20:35]
	ds_read_b128 v[174:177], v201 offset:4704
	ds_read_b128 v[140:143], v201 offset:64
	v_mfma_f32_32x32x16_bf16 v[52:67], v[136:139], v[178:181], v[52:67]
	ds_read_b128 v[206:209], v200 offset:36960
	ds_read_b128 v[136:139], v200 offset:41536
	v_mfma_f32_32x32x16_bf16 v[20:35], v[144:147], v[178:181], v[20:35]
	ds_read_b128 v[178:181], v200 offset:36928
	ds_read_b128 v[144:147], v201 offset:96
	s_waitcnt lgkmcnt(1)
	v_mfma_f32_32x32x16_bf16 v[52:67], v[140:143], v[178:181], v[52:67]
	s_waitcnt vmcnt(15)
	ds_write_b128 v198, v[128:131] offset:18432
	v_mfma_f32_32x32x16_bf16 v[36:51], v[140:143], v[136:139], v[36:51]
	s_waitcnt vmcnt(14)
	ds_write_b128 v198, v[120:123] offset:55296
	v_mfma_f32_32x32x16_bf16 v[20:35], v[116:119], v[178:181], v[20:35]
	s_waitcnt vmcnt(13)
	ds_write_b128 v196, v[112:115] offset:18432
	v_mfma_f32_32x32x16_bf16 v[4:19], v[116:119], v[136:139], v[4:19]
	s_waitcnt vmcnt(12)
	ds_write_b128 v196, v[104:107] offset:55296
	s_waitcnt lgkmcnt(4)
	v_mfma_f32_32x32x16_bf16 v[52:67], v[144:147], v[206:209], v[52:67]
	s_waitcnt vmcnt(11)
	ds_write_b128 v194, v[92:95] offset:18432
	v_mfma_f32_32x32x16_bf16 v[36:51], v[144:147], v[210:213], v[36:51]
	s_waitcnt vmcnt(10)
	ds_write_b128 v194, v[84:87] offset:55296
	v_mfma_f32_32x32x16_bf16 v[20:35], v[174:177], v[206:209], v[20:35]
	s_waitcnt vmcnt(9)
	ds_write_b128 v2, v[76:79] offset:18432
	v_mfma_f32_32x32x16_bf16 v[4:19], v[174:177], v[210:213], v[4:19]
	s_waitcnt vmcnt(8)
	ds_write_b128 v2, v[68:71] offset:55296
	s_waitcnt lgkmcnt(0)
	s_barrier
	global_load_dwordx4 v[136:139], v[160:161], off offset:1152
	global_load_dwordx4 v[128:131], v[0:1], off offset:1152
	global_load_dwordx4 v[116:119], v[162:163], off offset:1152
	global_load_dwordx4 v[104:107], v[152:153], off offset:1152
	global_load_dwordx4 v[92:95], v[164:165], off offset:1152
	global_load_dwordx4 v[84:87], v[154:155], off offset:1152
	global_load_dwordx4 v[76:79], v[166:167], off offset:1152
	global_load_dwordx4 v[68:71], v[156:157], off offset:1152
	ds_read_b128 v[112:115], v192
	ds_read_b128 v[120:123], v192 offset:32
	ds_read_b128 v[140:143], v192 offset:4608
	ds_read_b128 v[144:147], v192 offset:4640
	ds_read_b128 v[174:177], v191 offset:36864
	ds_read_b128 v[178:181], v191 offset:36896
	ds_read_b128 v[206:209], v191 offset:41472
	ds_read_b128 v[210:213], v191 offset:41504
	s_waitcnt lgkmcnt(3)
	v_mfma_f32_32x32x16_bf16 v[52:67], v[112:115], v[174:177], v[52:67]
	s_waitcnt lgkmcnt(1)
	v_mfma_f32_32x32x16_bf16 v[36:51], v[112:115], v[206:209], v[36:51]
	v_mfma_f32_32x32x16_bf16 v[4:19], v[140:143], v[206:209], v[4:19]
	s_waitcnt lgkmcnt(0)
	v_mfma_f32_32x32x16_bf16 v[36:51], v[120:123], v[210:213], v[36:51]
	v_mfma_f32_32x32x16_bf16 v[4:19], v[144:147], v[210:213], v[4:19]
	ds_read_b128 v[210:213], v191 offset:41568
	ds_read_b128 v[112:115], v192 offset:4672
	v_mfma_f32_32x32x16_bf16 v[20:35], v[140:143], v[174:177], v[20:35]
	ds_read_b128 v[174:177], v192 offset:4704
	ds_read_b128 v[140:143], v192 offset:64
	v_mfma_f32_32x32x16_bf16 v[52:67], v[120:123], v[178:181], v[52:67]
	ds_read_b128 v[206:209], v191 offset:36960
	ds_read_b128 v[120:123], v191 offset:41536
	v_mfma_f32_32x32x16_bf16 v[20:35], v[144:147], v[178:181], v[20:35]
	ds_read_b128 v[178:181], v191 offset:36928
	ds_read_b128 v[144:147], v192 offset:96
	s_waitcnt lgkmcnt(1)
	v_mfma_f32_32x32x16_bf16 v[52:67], v[140:143], v[178:181], v[52:67]
	s_waitcnt vmcnt(15)
	ds_write_b128 v198, v[132:135]
	v_mfma_f32_32x32x16_bf16 v[36:51], v[140:143], v[120:123], v[36:51]
	s_waitcnt vmcnt(14)
	ds_write_b128 v198, v[124:127] offset:36864
	v_mfma_f32_32x32x16_bf16 v[20:35], v[112:115], v[178:181], v[20:35]
	s_waitcnt vmcnt(13)
	ds_write_b128 v196, v[108:111]
	v_mfma_f32_32x32x16_bf16 v[4:19], v[112:115], v[120:123], v[4:19]
	s_waitcnt vmcnt(12)
	ds_write_b128 v196, v[100:103] offset:36864
	s_waitcnt lgkmcnt(4)
	v_mfma_f32_32x32x16_bf16 v[52:67], v[144:147], v[206:209], v[52:67]
	s_waitcnt vmcnt(11)
	ds_write_b128 v194, v[96:99]
	v_mfma_f32_32x32x16_bf16 v[36:51], v[144:147], v[210:213], v[36:51]
	s_waitcnt vmcnt(10)
	ds_write_b128 v194, v[88:91] offset:36864
	v_mfma_f32_32x32x16_bf16 v[20:35], v[174:177], v[206:209], v[20:35]
	s_waitcnt vmcnt(9)
	ds_write_b128 v2, v[80:83]
	v_mfma_f32_32x32x16_bf16 v[4:19], v[174:177], v[210:213], v[4:19]
	s_waitcnt vmcnt(8)
	ds_write_b128 v2, v[72:75] offset:36864
	s_waitcnt lgkmcnt(0)
	s_barrier
; #define MFMA(a, b, c) __builtin_amdgcn_mfma_f32_32x32x16_bf16((a), (b), (c), 0, 0, 0)
; template <class Epi, class ColV>
; DI void gemm_tile(const bf16_t* __restrict__ A, int lda, const bf16_t* __restrict__ Bt, int ldb, int K, int m0, int n0, unsigned char* smem, Epi epi, ColV colv, const bf16_t* __restrict__ HYT = nullptr) {
;     ...
;             if (HYT && kt >= 12) r[i] = *(const u32x4*)(HYT + (size_t)((kt - 12) * 64 + (id >> 4)) * NT + m0 + (id & 15) * 8);
;     ...
;     auto step = [&](int kt, u32x4 (&ldset)[8], const u32x4 (&stset)[8]) {
;         const int buf = kt & 1;
;         if (kt + 2 < nk) gload(ldset, kt + 2);
;         const bf16_t* Ab = As + (buf * 128 + 64 * wr + li) * LS + 8 * lh;
;         const bf16_t* Bb = Bs + (buf * 128 + 64 * wc + li) * LS + 8 * lh;
;         bf16x8 fa[2][2], fb[2][2], ga[2][2], gb[2][2];
; #pragma unroll
;         for (int k2 = 0; k2 < 2; ++k2) { fa[k2][0] = ld8(Ab + 16 * k2); fa[k2][1] = ld8(Ab + 32 * LS + 16 * k2); fb[k2][0] = ld8(Bb + 16 * k2); fb[k2][1] = ld8(Bb + 32 * LS + 16 * k2); }
;         __builtin_amdgcn_sched_barrier(0);
; #pragma unroll
;         for (int k2 = 0; k2 < 2; ++k2) {
;             acc[0][0] = MFMA(fa[k2][0], fb[k2][0], acc[0][0]); acc[0][1] = MFMA(fa[k2][0], fb[k2][1], acc[0][1]);
;             acc[1][0] = MFMA(fa[k2][1], fb[k2][0], acc[1][0]); acc[1][1] = MFMA(fa[k2][1], fb[k2][1], acc[1][1]);
;         }
; #pragma unroll
;         for (int k2 = 0; k2 < 2; ++k2) { const int ks = 2 + k2; ga[k2][0] = ld8(Ab + 16 * ks); ga[k2][1] = ld8(Ab + 32 * LS + 16 * ks); gb[k2][0] = ld8(Bb + 16 * ks); gb[k2][1] = ld8(Bb + 32 * LS + 16 * ks); }
; #pragma unroll
;         for (int k2 = 0; k2 < 2; ++k2) {
;             acc[0][0] = MFMA(ga[k2][0], gb[k2][0], acc[0][0]); acc[0][1] = MFMA(ga[k2][0], gb[k2][1], acc[0][1]);
;             acc[1][0] = MFMA(ga[k2][1], gb[k2][0], acc[1][0]); acc[1][1] = MFMA(ga[k2][1], gb[k2][1], acc[1][1]);
;         }
;         if (kt + 1 < nk) sstore(stset, buf ^ 1, kt + 1);
; #pragma unroll
;         for (int i = 0; i < 8; ++i) { __builtin_amdgcn_sched_group_barrier(0x008, 1, 0); __builtin_amdgcn_sched_group_barrier(0x100, 1, 0); }
; #pragma unroll
;         for (int i = 0; i < 8; ++i) { __builtin_amdgcn_sched_group_barrier(0x008, 1, 0); __builtin_amdgcn_sched_group_barrier(0x200, 1, 0); }
;         __builtin_amdgcn_sched_barrier(0);
;         __syncthreads();
;     };
	global_load_dwordx4 v[140:143], v[160:161], off offset:1280
	global_load_dwordx4 v[132:135], v[0:1], off offset:1280
	global_load_dwordx4 v[120:123], v[162:163], off offset:1280
	global_load_dwordx4 v[112:115], v[152:153], off offset:1280
	global_load_dwordx4 v[96:99], v[164:165], off offset:1280
	global_load_dwordx4 v[88:91], v[154:155], off offset:1280
	global_load_dwordx4 v[80:83], v[166:167], off offset:1280
	global_load_dwordx4 v[72:75], v[156:157], off offset:1280
	ds_read_b128 v[100:103], v201
	ds_read_b128 v[108:111], v201 offset:32
	ds_read_b128 v[124:127], v201 offset:4608
	ds_read_b128 v[144:147], v201 offset:4640
	ds_read_b128 v[174:177], v200 offset:36864
	ds_read_b128 v[178:181], v200 offset:36896
	ds_read_b128 v[206:209], v200 offset:41472
	ds_read_b128 v[210:213], v200 offset:41504
	s_waitcnt lgkmcnt(3)
	v_mfma_f32_32x32x16_bf16 v[52:67], v[100:103], v[174:177], v[52:67]
	s_waitcnt lgkmcnt(1)
	v_mfma_f32_32x32x16_bf16 v[36:51], v[100:103], v[206:209], v[36:51]
	v_mfma_f32_32x32x16_bf16 v[4:19], v[124:127], v[206:209], v[4:19]
	s_waitcnt lgkmcnt(0)
	v_mfma_f32_32x32x16_bf16 v[36:51], v[108:111], v[210:213], v[36:51]
	v_mfma_f32_32x32x16_bf16 v[4:19], v[144:147], v[210:213], v[4:19]
	ds_read_b128 v[210:213], v200 offset:41568
	ds_read_b128 v[100:103], v201 offset:4672
	v_mfma_f32_32x32x16_bf16 v[20:35], v[124:127], v[174:177], v[20:35]
	ds_read_b128 v[174:177], v201 offset:4704
	ds_read_b128 v[124:127], v201 offset:64
	v_mfma_f32_32x32x16_bf16 v[52:67], v[108:111], v[178:181], v[52:67]
	ds_read_b128 v[206:209], v200 offset:36960
	ds_read_b128 v[108:111], v200 offset:41536
	v_mfma_f32_32x32x16_bf16 v[20:35], v[144:147], v[178:181], v[20:35]
	ds_read_b128 v[178:181], v200 offset:36928
	ds_read_b128 v[144:147], v201 offset:96
	s_waitcnt lgkmcnt(1)
	v_mfma_f32_32x32x16_bf16 v[52:67], v[124:127], v[178:181], v[52:67]
	s_waitcnt vmcnt(15)
	ds_write_b128 v198, v[136:139] offset:18432
	v_mfma_f32_32x32x16_bf16 v[36:51], v[124:127], v[108:111], v[36:51]
	s_waitcnt vmcnt(14)
	ds_write_b128 v198, v[128:131] offset:55296
	v_mfma_f32_32x32x16_bf16 v[20:35], v[100:103], v[178:181], v[20:35]
	s_waitcnt vmcnt(13)
	ds_write_b128 v196, v[116:119] offset:18432
	v_mfma_f32_32x32x16_bf16 v[4:19], v[100:103], v[108:111], v[4:19]
	s_waitcnt vmcnt(12)
	ds_write_b128 v196, v[104:107] offset:55296
	s_waitcnt lgkmcnt(4)
	v_mfma_f32_32x32x16_bf16 v[52:67], v[144:147], v[206:209], v[52:67]
	s_waitcnt vmcnt(11)
	ds_write_b128 v194, v[92:95] offset:18432
	v_mfma_f32_32x32x16_bf16 v[36:51], v[144:147], v[210:213], v[36:51]
	s_waitcnt vmcnt(10)
	ds_write_b128 v194, v[84:87] offset:55296
	v_mfma_f32_32x32x16_bf16 v[20:35], v[174:177], v[206:209], v[20:35]
	s_waitcnt vmcnt(9)
	ds_write_b128 v2, v[76:79] offset:18432
	v_mfma_f32_32x32x16_bf16 v[4:19], v[174:177], v[210:213], v[4:19]
	s_waitcnt vmcnt(8)
	ds_write_b128 v2, v[68:71] offset:55296
	s_waitcnt lgkmcnt(0)
	s_barrier
	global_load_dwordx4 v[124:127], v[160:161], off offset:1408
	global_load_dwordx4 v[116:119], v[0:1], off offset:1408
	global_load_dwordx4 v[108:111], v[162:163], off offset:1408
	global_load_dwordx4 v[100:103], v[152:153], off offset:1408
	global_load_dwordx4 v[92:95], v[164:165], off offset:1408
	global_load_dwordx4 v[84:87], v[154:155], off offset:1408
	global_load_dwordx4 v[76:79], v[166:167], off offset:1408
	global_load_dwordx4 v[68:71], v[156:157], off offset:1408
	ds_read_b128 v[104:107], v192
	ds_read_b128 v[128:131], v192 offset:32
	ds_read_b128 v[136:139], v192 offset:4608
	ds_read_b128 v[144:147], v192 offset:4640
	ds_read_b128 v[160:163], v191 offset:36864
	ds_read_b128 v[164:167], v191 offset:36896
	ds_read_b128 v[174:177], v191 offset:41472
	ds_read_b128 v[178:181], v191 offset:41504
	s_waitcnt lgkmcnt(3)
	v_mfma_f32_32x32x16_bf16 v[52:67], v[104:107], v[160:163], v[52:67]
	s_waitcnt lgkmcnt(1)
	v_mfma_f32_32x32x16_bf16 v[36:51], v[104:107], v[174:177], v[36:51]
	v_mfma_f32_32x32x16_bf16 v[4:19], v[136:139], v[174:177], v[4:19]
	s_waitcnt lgkmcnt(0)
	v_mfma_f32_32x32x16_bf16 v[36:51], v[128:131], v[178:181], v[36:51]
	v_mfma_f32_32x32x16_bf16 v[4:19], v[144:147], v[178:181], v[4:19]
	ds_read_b128 v[178:181], v191 offset:41568
	ds_read_b128 v[104:107], v192 offset:4672
	v_mfma_f32_32x32x16_bf16 v[20:35], v[136:139], v[160:163], v[20:35]
	ds_read_b128 v[160:163], v192 offset:4704
	ds_read_b128 v[136:139], v192 offset:64
	v_mfma_f32_32x32x16_bf16 v[52:67], v[128:131], v[164:167], v[52:67]
	ds_read_b128 v[174:177], v191 offset:36960
	ds_read_b128 v[128:131], v191 offset:41536
	v_mfma_f32_32x32x16_bf16 v[20:35], v[144:147], v[164:167], v[20:35]
	ds_read_b128 v[164:167], v191 offset:36928
	ds_read_b128 v[144:147], v192 offset:96
	s_waitcnt lgkmcnt(1)
	v_mfma_f32_32x32x16_bf16 v[52:67], v[136:139], v[164:167], v[52:67]
	s_waitcnt vmcnt(15)
	ds_write_b128 v198, v[140:143]
	v_mfma_f32_32x32x16_bf16 v[36:51], v[136:139], v[128:131], v[36:51]
	s_waitcnt vmcnt(14)
	ds_write_b128 v198, v[132:135] offset:36864
	v_mfma_f32_32x32x16_bf16 v[20:35], v[104:107], v[164:167], v[20:35]
	s_waitcnt vmcnt(13)
	ds_write_b128 v196, v[120:123]
	v_mfma_f32_32x32x16_bf16 v[4:19], v[104:107], v[128:131], v[4:19]
	s_waitcnt vmcnt(12)
	ds_write_b128 v196, v[112:115] offset:36864
	s_waitcnt lgkmcnt(4)
	v_mfma_f32_32x32x16_bf16 v[52:67], v[144:147], v[174:177], v[52:67]
	s_waitcnt vmcnt(11)
	ds_write_b128 v194, v[96:99]
	v_mfma_f32_32x32x16_bf16 v[36:51], v[144:147], v[178:181], v[36:51]
	s_waitcnt vmcnt(10)
	ds_write_b128 v194, v[88:91] offset:36864
	v_mfma_f32_32x32x16_bf16 v[20:35], v[160:163], v[174:177], v[20:35]
	s_waitcnt vmcnt(9)
	ds_write_b128 v2, v[80:83]
	v_mfma_f32_32x32x16_bf16 v[4:19], v[160:163], v[178:181], v[4:19]
	s_waitcnt vmcnt(8)
	ds_write_b128 v2, v[72:75] offset:36864
	v_mad_i64_i32 v[96:97], s[40:41], v202, s43, v[158:159]
	v_mad_i64_i32 v[98:99], s[40:41], v205, s43, v[158:159]
	v_mad_i64_i32 v[112:113], s[40:41], v204, s43, v[158:159]
	v_mad_i64_i32 v[132:133], s[40:41], v203, s43, v[158:159]
	s_waitcnt lgkmcnt(0)
	s_barrier
; template <class Epi, class ColV>
; DI void gemm_tile(const bf16_t* __restrict__ A, int lda, const bf16_t* __restrict__ Bt, int ldb, int K, int m0, int n0, unsigned char* smem, Epi epi, ColV colv, const bf16_t* __restrict__ HYT = nullptr) {
;     ...
;             if (HYT && kt >= 12) r[i] = *(const u32x4*)(HYT + (size_t)((kt - 12) * 64 + (id >> 4)) * NT + m0 + (id & 15) * 8);
;             else r[i] = *(const u32x4*)(A + (size_t)(m0 + row) * lda + kt * 64 + kc * 8);
;             r[4 + i] = *(const u32x4*)(Bt + (size_t)(n0 + row) * ldb + kt * 64 + kc * 8); }
;     };
;     auto sstore = [&](const u32x4 (&r)[8], int buf, int kt) {
; #pragma unroll
;         for (int i = 0; i < 4; ++i) { int id = tid + 256 * i, row = id >> 3, kc = id & 7;
;             if (HYT && kt >= 12) { const int kk = id >> 4, rr = (id & 15) * 8; bf16_t* d = As + (buf * 128 + rr) * LS + kk; const bf16x8 v = __builtin_bit_cast(bf16x8, r[i]);
; #pragma unroll
;                 for (int e = 0; e < 8; ++e) d[e * LS] = (bf16_t)v[e]; }
;     ...
;     auto step = [&](int kt, u32x4 (&ldset)[8], const u32x4 (&stset)[8]) {
;         const int buf = kt & 1;
;         if (kt + 2 < nk) gload(ldset, kt + 2);
;         const bf16_t* Ab = As + (buf * 128 + 64 * wr + li) * LS + 8 * lh;
;         const bf16_t* Bb = Bs + (buf * 128 + 64 * wc + li) * LS + 8 * lh;
;         bf16x8 fa[2][2], fb[2][2], ga[2][2], gb[2][2];
; #pragma unroll
;         for (int k2 = 0; k2 < 2; ++k2) { fa[k2][0] = ld8(Ab + 16 * k2); fa[k2][1] = ld8(Ab + 32 * LS + 16 * k2); fb[k2][0] = ld8(Bb + 16 * k2); fb[k2][1] = ld8(Bb + 32 * LS + 16 * k2); }
;         __builtin_amdgcn_sched_barrier(0);
; #pragma unroll
;         for (int k2 = 0; k2 < 2; ++k2) {
;             acc[0][0] = MFMA(fa[k2][0], fb[k2][0], acc[0][0]); acc[0][1] = MFMA(fa[k2][0], fb[k2][1], acc[0][1]);
;             acc[1][0] = MFMA(fa[k2][1], fb[k2][0], acc[1][0]); acc[1][1] = MFMA(fa[k2][1], fb[k2][1], acc[1][1]);
;         }
; #pragma unroll
;         for (int k2 = 0; k2 < 2; ++k2) { const int ks = 2 + k2; ga[k2][0] = ld8(Ab + 16 * ks); ga[k2][1] = ld8(Ab + 32 * LS + 16 * ks); gb[k2][0] = ld8(Bb + 16 * ks); gb[k2][1] = ld8(Bb + 32 * LS + 16 * ks); }
; #pragma unroll
;         for (int k2 = 0; k2 < 2; ++k2) {
;             acc[0][0] = MFMA(ga[k2][0], gb[k2][0], acc[0][0]); acc[0][1] = MFMA(ga[k2][0], gb[k2][1], acc[0][1]);
	global_load_dwordx4 v[104:107], v[0:1], off offset:1536
	global_load_dwordx4 v[88:91], v[152:153], off offset:1536
	global_load_dwordx4 v[80:83], v[154:155], off offset:1536
	global_load_dwordx4 v[72:75], v[156:157], off offset:1536
	global_load_dwordx4 v[128:131], v[96:97], off
	global_load_dwordx4 v[120:123], v[98:99], off
	ds_read_b128 v[136:139], v201 offset:32
	global_load_dwordx4 v[112:115], v[112:113], off
	ds_read_b128 v[140:143], v201 offset:4608
	global_load_dwordx4 v[96:99], v[132:133], off
	ds_read_b128 v[132:135], v201
	ds_read_b128 v[144:147], v201 offset:4640
	ds_read_b128 v[160:163], v200 offset:36864
	ds_read_b128 v[164:167], v200 offset:36896
	ds_read_b128 v[174:177], v200 offset:41472
	ds_read_b128 v[178:181], v200 offset:41504
	s_waitcnt lgkmcnt(3)
	v_mfma_f32_32x32x16_bf16 v[52:67], v[132:135], v[160:163], v[52:67]
	s_waitcnt lgkmcnt(1)
	v_mfma_f32_32x32x16_bf16 v[36:51], v[132:135], v[174:177], v[36:51]
	v_mfma_f32_32x32x16_bf16 v[4:19], v[140:143], v[174:177], v[4:19]
	s_waitcnt lgkmcnt(0)
	v_mfma_f32_32x32x16_bf16 v[36:51], v[136:139], v[178:181], v[36:51]
	v_mfma_f32_32x32x16_bf16 v[4:19], v[144:147], v[178:181], v[4:19]
	ds_read_b128 v[178:181], v200 offset:41568
	ds_read_b128 v[132:135], v201 offset:4672
	v_mfma_f32_32x32x16_bf16 v[20:35], v[140:143], v[160:163], v[20:35]
	ds_read_b128 v[160:163], v201 offset:4704
	ds_read_b128 v[140:143], v201 offset:64
	v_mfma_f32_32x32x16_bf16 v[52:67], v[136:139], v[164:167], v[52:67]
	ds_read_b128 v[174:177], v200 offset:36960
	ds_read_b128 v[136:139], v200 offset:41536
	v_mfma_f32_32x32x16_bf16 v[20:35], v[144:147], v[164:167], v[20:35]
	ds_read_b128 v[164:167], v200 offset:36928
	ds_read_b128 v[144:147], v201 offset:96
	s_waitcnt lgkmcnt(1)
	v_mfma_f32_32x32x16_bf16 v[52:67], v[140:143], v[164:167], v[52:67]
	s_waitcnt vmcnt(15)
	ds_write_b128 v198, v[124:127] offset:18432
	v_mfma_f32_32x32x16_bf16 v[36:51], v[140:143], v[136:139], v[36:51]
	s_waitcnt vmcnt(14)
	ds_write_b128 v198, v[116:119] offset:55296
	v_mfma_f32_32x32x16_bf16 v[20:35], v[132:135], v[164:167], v[20:35]
	s_waitcnt vmcnt(13)
	ds_write_b128 v196, v[108:111] offset:18432
	v_mfma_f32_32x32x16_bf16 v[4:19], v[132:135], v[136:139], v[4:19]
	s_waitcnt vmcnt(12)
	ds_write_b128 v196, v[100:103] offset:55296
	s_waitcnt lgkmcnt(4)
	v_mfma_f32_32x32x16_bf16 v[52:67], v[144:147], v[174:177], v[52:67]
	s_waitcnt vmcnt(11)
	ds_write_b128 v194, v[92:95] offset:18432
	v_mfma_f32_32x32x16_bf16 v[36:51], v[144:147], v[178:181], v[36:51]
	s_waitcnt vmcnt(10)
	ds_write_b128 v194, v[84:87] offset:55296
	v_mfma_f32_32x32x16_bf16 v[20:35], v[160:163], v[174:177], v[20:35]
	s_waitcnt vmcnt(9)
	ds_write_b128 v2, v[76:79] offset:18432
	v_mfma_f32_32x32x16_bf16 v[4:19], v[160:163], v[178:181], v[4:19]
	s_waitcnt vmcnt(8)
	ds_write_b128 v2, v[68:71] offset:55296
	v_add_u32_e32 v68, 64, v202
	v_mad_i64_i32 v[92:93], s[40:41], v68, s43, v[158:159]
	v_add_u32_e32 v68, 64, v205
	v_mad_i64_i32 v[94:95], s[40:41], v68, s43, v[158:159]
	v_add_u32_e32 v68, 64, v204
	v_mad_i64_i32 v[108:109], s[40:41], v68, s43, v[158:159]
	v_add_u32_e32 v68, 64, v203
	v_mad_i64_i32 v[132:133], s[40:41], v68, s43, v[158:159]
	s_waitcnt lgkmcnt(0)
	s_barrier
	global_load_dwordx4 v[100:103], v[0:1], off offset:1664
	global_load_dwordx4 v[84:87], v[152:153], off offset:1664
	global_load_dwordx4 v[76:79], v[154:155], off offset:1664
	global_load_dwordx4 v[68:71], v[156:157], off offset:1664
	global_load_dwordx4 v[124:127], v[92:93], off
	global_load_dwordx4 v[116:119], v[94:95], off
	ds_read_b128 v[136:139], v192 offset:32
	global_load_dwordx4 v[108:111], v[108:109], off
	ds_read_b128 v[140:143], v192 offset:4608
	global_load_dwordx4 v[92:95], v[132:133], off
	ds_read_b128 v[132:135], v192
	ds_read_b128 v[144:147], v192 offset:4640
	ds_read_b128 v[160:163], v191 offset:36864
	ds_read_b128 v[164:167], v191 offset:36896
	ds_read_b128 v[174:177], v191 offset:41472
	ds_read_b128 v[178:181], v191 offset:41504
	s_waitcnt lgkmcnt(3)
	v_mfma_f32_32x32x16_bf16 v[52:67], v[132:135], v[160:163], v[52:67]
	s_waitcnt lgkmcnt(1)
	v_mfma_f32_32x32x16_bf16 v[36:51], v[132:135], v[174:177], v[36:51]
	v_mfma_f32_32x32x16_bf16 v[4:19], v[140:143], v[174:177], v[4:19]
	s_waitcnt lgkmcnt(0)
	v_mfma_f32_32x32x16_bf16 v[36:51], v[136:139], v[178:181], v[36:51]
	v_mfma_f32_32x32x16_bf16 v[4:19], v[144:147], v[178:181], v[4:19]
	ds_read_b128 v[178:181], v191 offset:41568
	ds_read_b128 v[132:135], v192 offset:4672
	v_mfma_f32_32x32x16_bf16 v[20:35], v[140:143], v[160:163], v[20:35]
	ds_read_b128 v[160:163], v192 offset:4704
	ds_read_b128 v[140:143], v192 offset:64
	v_mfma_f32_32x32x16_bf16 v[52:67], v[136:139], v[164:167], v[52:67]
	ds_read_b128 v[174:177], v191 offset:36960
	ds_read_b128 v[136:139], v191 offset:41536
	v_mfma_f32_32x32x16_bf16 v[20:35], v[144:147], v[164:167], v[20:35]
	ds_read_b128 v[164:167], v191 offset:36928
	ds_read_b128 v[144:147], v192 offset:96
	s_waitcnt lgkmcnt(1)
	v_mfma_f32_32x32x16_bf16 v[52:67], v[140:143], v[164:167], v[52:67]
	s_waitcnt vmcnt(11)
	ds_write_b16 v199, v128
	v_mfma_f32_32x32x16_bf16 v[36:51], v[140:143], v[136:139], v[36:51]
	ds_write_b16_d16_hi v199, v128 offset:144
	v_mfma_f32_32x32x16_bf16 v[20:35], v[132:135], v[164:167], v[20:35]
	ds_write_b16 v199, v129 offset:288
	v_mfma_f32_32x32x16_bf16 v[4:19], v[132:135], v[136:139], v[4:19]
	ds_write_b16_d16_hi v199, v129 offset:432
	s_waitcnt lgkmcnt(4)
; template <class Epi, class ColV>
; DI void gemm_tile(const bf16_t* __restrict__ A, int lda, const bf16_t* __restrict__ Bt, int ldb, int K, int m0, int n0, unsigned char* smem, Epi epi, ColV colv, const bf16_t* __restrict__ HYT = nullptr) {
;     ...
;             if (HYT && kt >= 12) { const int kk = id >> 4, rr = (id & 15) * 8; bf16_t* d = As + (buf * 128 + rr) * LS + kk; const bf16x8 v = __builtin_bit_cast(bf16x8, r[i]);
; #pragma unroll
;                 for (int e = 0; e < 8; ++e) d[e * LS] = (bf16_t)v[e]; }
;     ...
;     auto step = [&](int kt, u32x4 (&ldset)[8], const u32x4 (&stset)[8]) {
;         const int buf = kt & 1;
;         if (kt + 2 < nk) gload(ldset, kt + 2);
;         const bf16_t* Ab = As + (buf * 128 + 64 * wr + li) * LS + 8 * lh;
;         const bf16_t* Bb = Bs + (buf * 128 + 64 * wc + li) * LS + 8 * lh;
;         bf16x8 fa[2][2], fb[2][2], ga[2][2], gb[2][2];
; #pragma unroll
;         for (int k2 = 0; k2 < 2; ++k2) { fa[k2][0] = ld8(Ab + 16 * k2); fa[k2][1] = ld8(Ab + 32 * LS + 16 * k2); fb[k2][0] = ld8(Bb + 16 * k2); fb[k2][1] = ld8(Bb + 32 * LS + 16 * k2); }
;         __builtin_amdgcn_sched_barrier(0);
; #pragma unroll
;         for (int k2 = 0; k2 < 2; ++k2) {
;             acc[0][0] = MFMA(fa[k2][0], fb[k2][0], acc[0][0]); acc[0][1] = MFMA(fa[k2][0], fb[k2][1], acc[0][1]);
;             acc[1][0] = MFMA(fa[k2][1], fb[k2][0], acc[1][0]); acc[1][1] = MFMA(fa[k2][1], fb[k2][1], acc[1][1]);
;         }
; #pragma unroll
;         for (int k2 = 0; k2 < 2; ++k2) { const int ks = 2 + k2; ga[k2][0] = ld8(Ab + 16 * ks); ga[k2][1] = ld8(Ab + 32 * LS + 16 * ks); gb[k2][0] = ld8(Bb + 16 * ks); gb[k2][1] = ld8(Bb + 32 * LS + 16 * ks); }
; #pragma unroll
;         for (int k2 = 0; k2 < 2; ++k2) {
;             acc[0][0] = MFMA(ga[k2][0], gb[k2][0], acc[0][0]); acc[0][1] = MFMA(ga[k2][0], gb[k2][1], acc[0][1]);
;             acc[1][0] = MFMA(ga[k2][1], gb[k2][0], acc[1][0]); acc[1][1] = MFMA(ga[k2][1], gb[k2][1], acc[1][1]);
;         }
;         if (kt + 1 < nk) sstore(stset, buf ^ 1, kt + 1);
; #pragma unroll
;         for (int i = 0; i < 8; ++i) { __builtin_amdgcn_sched_group_barrier(0x008, 1, 0); __builtin_amdgcn_sched_group_barrier(0x100, 1, 0); }
; #pragma unroll
;         for (int i = 0; i < 8; ++i) { __builtin_amdgcn_sched_group_barrier(0x008, 1, 0); __builtin_amdgcn_sched_group_barrier(0x200, 1, 0); }
;         __builtin_amdgcn_sched_barrier(0);
	v_mfma_f32_32x32x16_bf16 v[52:67], v[144:147], v[174:177], v[52:67]
	ds_write_b16 v199, v130 offset:576
	v_mfma_f32_32x32x16_bf16 v[36:51], v[144:147], v[178:181], v[36:51]
	ds_write_b16_d16_hi v199, v130 offset:720
	v_mfma_f32_32x32x16_bf16 v[20:35], v[160:163], v[174:177], v[20:35]
	ds_write_b16 v199, v131 offset:864
	v_mfma_f32_32x32x16_bf16 v[4:19], v[160:163], v[178:181], v[4:19]
	ds_write_b16_d16_hi v199, v131 offset:1008
	ds_write_b128 v198, v[104:107] offset:36864
	s_waitcnt vmcnt(10)
	ds_write_b16 v197, v120
	ds_write_b16_d16_hi v197, v120 offset:144
	ds_write_b16 v197, v121 offset:288
	ds_write_b16_d16_hi v197, v121 offset:432
	ds_write_b16 v197, v122 offset:576
	ds_write_b16_d16_hi v197, v122 offset:720
	ds_write_b16 v197, v123 offset:864
	ds_write_b16_d16_hi v197, v123 offset:1008
	ds_write_b128 v196, v[88:91] offset:36864
	s_waitcnt vmcnt(9)
	ds_write_b16 v195, v112
	ds_write_b16_d16_hi v195, v112 offset:144
	ds_write_b16 v195, v113 offset:288
	ds_write_b16_d16_hi v195, v113 offset:432
	ds_write_b16 v195, v114 offset:576
	ds_write_b16_d16_hi v195, v114 offset:720
	ds_write_b16 v195, v115 offset:864
	ds_write_b16_d16_hi v195, v115 offset:1008
	ds_write_b128 v194, v[80:83] offset:36864
	s_waitcnt vmcnt(8)
	ds_write_b16 v193, v96
	ds_write_b16_d16_hi v193, v96 offset:144
	ds_write_b16 v193, v97 offset:288
	ds_write_b16_d16_hi v193, v97 offset:432
	ds_write_b16 v193, v98 offset:576
	ds_write_b16_d16_hi v193, v98 offset:720
	ds_write_b16 v193, v99 offset:864
	ds_write_b16_d16_hi v193, v99 offset:1008
	ds_write_b128 v2, v[72:75] offset:36864
	v_add_u32_e32 v72, 0x80, v202
	v_mad_i64_i32 v[96:97], s[40:41], v72, s43, v[158:159]
	v_add_u32_e32 v72, 0x80, v205
	v_mad_i64_i32 v[98:99], s[40:41], v72, s43, v[158:159]
	v_add_u32_e32 v72, 0x80, v204
	v_mad_i64_i32 v[112:113], s[40:41], v72, s43, v[158:159]
	v_add_u32_e32 v72, 0x80, v203
	v_mad_i64_i32 v[132:133], s[40:41], v72, s43, v[158:159]
	s_waitcnt lgkmcnt(0)
	s_barrier
	global_load_dwordx4 v[104:107], v[0:1], off offset:1792
	global_load_dwordx4 v[88:91], v[152:153], off offset:1792
	global_load_dwordx4 v[80:83], v[154:155], off offset:1792
	global_load_dwordx4 v[72:75], v[156:157], off offset:1792
	global_load_dwordx4 v[128:131], v[96:97], off
	global_load_dwordx4 v[120:123], v[98:99], off
	ds_read_b128 v[136:139], v201 offset:32
	global_load_dwordx4 v[112:115], v[112:113], off
	ds_read_b128 v[140:143], v201 offset:4608
	global_load_dwordx4 v[96:99], v[132:133], off
	ds_read_b128 v[132:135], v201
	ds_read_b128 v[144:147], v201 offset:4640
	ds_read_b128 v[160:163], v200 offset:36864
	ds_read_b128 v[164:167], v200 offset:36896
	ds_read_b128 v[174:177], v200 offset:41472
	ds_read_b128 v[178:181], v200 offset:41504
	s_waitcnt lgkmcnt(3)
	v_mfma_f32_32x32x16_bf16 v[52:67], v[132:135], v[160:163], v[52:67]
	s_waitcnt lgkmcnt(1)
	v_mfma_f32_32x32x16_bf16 v[36:51], v[132:135], v[174:177], v[36:51]
	v_mfma_f32_32x32x16_bf16 v[4:19], v[140:143], v[174:177], v[4:19]
	s_waitcnt lgkmcnt(0)
	v_mfma_f32_32x32x16_bf16 v[36:51], v[136:139], v[178:181], v[36:51]
	v_mfma_f32_32x32x16_bf16 v[4:19], v[144:147], v[178:181], v[4:19]
	ds_read_b128 v[178:181], v200 offset:41568
	ds_read_b128 v[132:135], v201 offset:4672
	v_mfma_f32_32x32x16_bf16 v[20:35], v[140:143], v[160:163], v[20:35]
	ds_read_b128 v[160:163], v201 offset:4704
	ds_read_b128 v[140:143], v201 offset:64
	v_mfma_f32_32x32x16_bf16 v[52:67], v[136:139], v[164:167], v[52:67]
	ds_read_b128 v[174:177], v200 offset:36960
	ds_read_b128 v[136:139], v200 offset:41536
	v_mfma_f32_32x32x16_bf16 v[20:35], v[144:147], v[164:167], v[20:35]
	ds_read_b128 v[164:167], v200 offset:36928
	ds_read_b128 v[144:147], v201 offset:96
	s_waitcnt lgkmcnt(1)
	v_mfma_f32_32x32x16_bf16 v[52:67], v[140:143], v[164:167], v[52:67]
	s_waitcnt vmcnt(11)
	ds_write_b16 v199, v124 offset:18432
	v_mfma_f32_32x32x16_bf16 v[36:51], v[140:143], v[136:139], v[36:51]
	ds_write_b16_d16_hi v199, v124 offset:18576
	v_mfma_f32_32x32x16_bf16 v[20:35], v[132:135], v[164:167], v[20:35]
	ds_write_b16 v199, v125 offset:18720
	v_mfma_f32_32x32x16_bf16 v[4:19], v[132:135], v[136:139], v[4:19]
	ds_write_b16_d16_hi v199, v125 offset:18864
	s_waitcnt lgkmcnt(4)
	v_mfma_f32_32x32x16_bf16 v[52:67], v[144:147], v[174:177], v[52:67]
	ds_write_b16 v199, v126 offset:19008
	v_mfma_f32_32x32x16_bf16 v[36:51], v[144:147], v[178:181], v[36:51]
	ds_write_b16_d16_hi v199, v126 offset:19152
	v_mfma_f32_32x32x16_bf16 v[20:35], v[160:163], v[174:177], v[20:35]
	ds_write_b16 v199, v127 offset:19296
	v_mfma_f32_32x32x16_bf16 v[4:19], v[160:163], v[178:181], v[4:19]
	ds_write_b16_d16_hi v199, v127 offset:19440
	ds_write_b128 v198, v[100:103] offset:55296
	s_waitcnt vmcnt(10)
	ds_write_b16 v197, v116 offset:18432
	ds_write_b16_d16_hi v197, v116 offset:18576
	ds_write_b16 v197, v117 offset:18720
	ds_write_b16_d16_hi v197, v117 offset:18864
	ds_write_b16 v197, v118 offset:19008
	ds_write_b16_d16_hi v197, v118 offset:19152
	ds_write_b16 v197, v119 offset:19296
	ds_write_b16_d16_hi v197, v119 offset:19440
	ds_write_b128 v196, v[84:87] offset:55296
	s_waitcnt vmcnt(9)
	ds_write_b16 v195, v108 offset:18432
	ds_write_b16_d16_hi v195, v108 offset:18576
	ds_write_b16 v195, v109 offset:18720
	ds_write_b16_d16_hi v195, v109 offset:18864
	ds_write_b16 v195, v110 offset:19008
	ds_write_b16_d16_hi v195, v110 offset:19152
	ds_write_b16 v195, v111 offset:19296
	ds_write_b16_d16_hi v195, v111 offset:19440
	ds_write_b128 v194, v[76:79] offset:55296
	s_waitcnt vmcnt(8)
	ds_write_b16 v193, v92 offset:18432
	ds_write_b16_d16_hi v193, v92 offset:18576
	ds_write_b16 v193, v93 offset:18720
	ds_write_b16_d16_hi v193, v93 offset:18864
	ds_write_b16 v193, v94 offset:19008
	ds_write_b16_d16_hi v193, v94 offset:19152
	ds_write_b16 v193, v95 offset:19296
	ds_write_b16_d16_hi v193, v95 offset:19440
	ds_write_b128 v2, v[68:71] offset:55296
	v_add_u32_e32 v68, 0xc0, v202
	v_mad_i64_i32 v[92:93], s[40:41], v68, s43, v[158:159]
	v_add_u32_e32 v68, 0xc0, v205
	s_waitcnt lgkmcnt(0)
	s_barrier
; template <class Epi, class ColV>
; DI void gemm_tile(const bf16_t* __restrict__ A, int lda, const bf16_t* __restrict__ Bt, int ldb, int K, int m0, int n0, unsigned char* smem, Epi epi, ColV colv, const bf16_t* __restrict__ HYT = nullptr) {
;     ...
;             if (HYT && kt >= 12) { const int kk = id >> 4, rr = (id & 15) * 8; bf16_t* d = As + (buf * 128 + rr) * LS + kk; const bf16x8 v = __builtin_bit_cast(bf16x8, r[i]);
; #pragma unroll
;                 for (int e = 0; e < 8; ++e) d[e * LS] = (bf16_t)v[e]; }
;     ...
;     auto step = [&](int kt, u32x4 (&ldset)[8], const u32x4 (&stset)[8]) {
;         const int buf = kt & 1;
;         if (kt + 2 < nk) gload(ldset, kt + 2);
;         const bf16_t* Ab = As + (buf * 128 + 64 * wr + li) * LS + 8 * lh;
;         const bf16_t* Bb = Bs + (buf * 128 + 64 * wc + li) * LS + 8 * lh;
;         bf16x8 fa[2][2], fb[2][2], ga[2][2], gb[2][2];
; #pragma unroll
;         for (int k2 = 0; k2 < 2; ++k2) { fa[k2][0] = ld8(Ab + 16 * k2); fa[k2][1] = ld8(Ab + 32 * LS + 16 * k2); fb[k2][0] = ld8(Bb + 16 * k2); fb[k2][1] = ld8(Bb + 32 * LS + 16 * k2); }
;         __builtin_amdgcn_sched_barrier(0);
; #pragma unroll
;         for (int k2 = 0; k2 < 2; ++k2) {
;             acc[0][0] = MFMA(fa[k2][0], fb[k2][0], acc[0][0]); acc[0][1] = MFMA(fa[k2][0], fb[k2][1], acc[0][1]);
;             acc[1][0] = MFMA(fa[k2][1], fb[k2][0], acc[1][0]); acc[1][1] = MFMA(fa[k2][1], fb[k2][1], acc[1][1]);
;         }
; #pragma unroll
;         for (int k2 = 0; k2 < 2; ++k2) { const int ks = 2 + k2; ga[k2][0] = ld8(Ab + 16 * ks); ga[k2][1] = ld8(Ab + 32 * LS + 16 * ks); gb[k2][0] = ld8(Bb + 16 * ks); gb[k2][1] = ld8(Bb + 32 * LS + 16 * ks); }
; #pragma unroll
;         for (int k2 = 0; k2 < 2; ++k2) {
;             acc[0][0] = MFMA(ga[k2][0], gb[k2][0], acc[0][0]); acc[0][1] = MFMA(ga[k2][0], gb[k2][1], acc[0][1]);
;             acc[1][0] = MFMA(ga[k2][1], gb[k2][0], acc[1][0]); acc[1][1] = MFMA(ga[k2][1], gb[k2][1], acc[1][1]);
;         }
;         if (kt + 1 < nk) sstore(stset, buf ^ 1, kt + 1);
; #pragma unroll
;         for (int i = 0; i < 8; ++i) { __builtin_amdgcn_sched_group_barrier(0x008, 1, 0); __builtin_amdgcn_sched_group_barrier(0x100, 1, 0); }
; #pragma unroll
;         for (int i = 0; i < 8; ++i) { __builtin_amdgcn_sched_group_barrier(0x008, 1, 0); __builtin_amdgcn_sched_group_barrier(0x200, 1, 0); }
;         __builtin_amdgcn_sched_barrier(0);
	v_mad_i64_i32 v[94:95], s[40:41], v68, s43, v[158:159]
	global_load_dwordx4 v[100:103], v[0:1], off offset:1920
	v_add_u32_e32 v0, 0xc0, v204
	v_add_u32_e32 v68, 0xc0, v203
	v_mad_i64_i32 v[0:1], s[40:41], v0, s43, v[158:159]
	v_mad_i64_i32 v[132:133], s[40:41], v68, s43, v[158:159]
	global_load_dwordx4 v[84:87], v[152:153], off offset:1920
	global_load_dwordx4 v[76:79], v[154:155], off offset:1920
	global_load_dwordx4 v[68:71], v[156:157], off offset:1920
	global_load_dwordx4 v[124:127], v[92:93], off
	global_load_dwordx4 v[116:119], v[94:95], off
	global_load_dwordx4 v[108:111], v[0:1], off
	ds_read_b128 v[136:139], v192 offset:32
	global_load_dwordx4 v[92:95], v[132:133], off
	ds_read_b128 v[132:135], v192
	ds_read_b128 v[140:143], v192 offset:4608
	ds_read_b128 v[144:147], v192 offset:4640
	ds_read_b128 v[152:155], v191 offset:36864
	ds_read_b128 v[156:159], v191 offset:36896
	ds_read_b128 v[160:163], v191 offset:41472
	ds_read_b128 v[164:167], v191 offset:41504
	s_waitcnt lgkmcnt(3)
	v_mfma_f32_32x32x16_bf16 v[52:67], v[132:135], v[152:155], v[52:67]
	s_waitcnt lgkmcnt(1)
	v_mfma_f32_32x32x16_bf16 v[36:51], v[132:135], v[160:163], v[36:51]
	v_mfma_f32_32x32x16_bf16 v[4:19], v[140:143], v[160:163], v[4:19]
	s_waitcnt lgkmcnt(0)
	v_mfma_f32_32x32x16_bf16 v[36:51], v[136:139], v[164:167], v[36:51]
	v_mfma_f32_32x32x16_bf16 v[4:19], v[144:147], v[164:167], v[4:19]
	ds_read_b128 v[164:167], v191 offset:41568
	ds_read_b128 v[132:135], v192 offset:4672
	v_mfma_f32_32x32x16_bf16 v[20:35], v[140:143], v[152:155], v[20:35]
	ds_read_b128 v[152:155], v192 offset:4704
	ds_read_b128 v[140:143], v192 offset:64
	v_mfma_f32_32x32x16_bf16 v[52:67], v[136:139], v[156:159], v[52:67]
	ds_read_b128 v[160:163], v191 offset:36960
	ds_read_b128 v[136:139], v191 offset:41536
	v_mfma_f32_32x32x16_bf16 v[20:35], v[144:147], v[156:159], v[20:35]
	ds_read_b128 v[156:159], v191 offset:36928
	ds_read_b128 v[144:147], v192 offset:96
	s_waitcnt lgkmcnt(1)
	v_mfma_f32_32x32x16_bf16 v[52:67], v[140:143], v[156:159], v[52:67]
	s_waitcnt vmcnt(11)
	ds_write_b16 v199, v128
	v_mfma_f32_32x32x16_bf16 v[36:51], v[140:143], v[136:139], v[36:51]
	ds_write_b16_d16_hi v199, v128 offset:144
	v_mfma_f32_32x32x16_bf16 v[20:35], v[132:135], v[156:159], v[20:35]
	ds_write_b16 v199, v129 offset:288
	v_mfma_f32_32x32x16_bf16 v[4:19], v[132:135], v[136:139], v[4:19]
	ds_write_b16_d16_hi v199, v129 offset:432
	s_waitcnt lgkmcnt(4)
	v_mfma_f32_32x32x16_bf16 v[52:67], v[144:147], v[160:163], v[52:67]
	ds_write_b16 v199, v130 offset:576
	v_mfma_f32_32x32x16_bf16 v[36:51], v[144:147], v[164:167], v[36:51]
	ds_write_b16_d16_hi v199, v130 offset:720
	v_mfma_f32_32x32x16_bf16 v[20:35], v[152:155], v[160:163], v[20:35]
	ds_write_b16 v199, v131 offset:864
	v_mfma_f32_32x32x16_bf16 v[4:19], v[152:155], v[164:167], v[4:19]
	ds_write_b16_d16_hi v199, v131 offset:1008
	ds_write_b128 v198, v[104:107] offset:36864
	s_waitcnt vmcnt(10)
	ds_write_b16 v197, v120
	ds_write_b16_d16_hi v197, v120 offset:144
	ds_write_b16 v197, v121 offset:288
	ds_write_b16_d16_hi v197, v121 offset:432
	ds_write_b16 v197, v122 offset:576
	ds_write_b16_d16_hi v197, v122 offset:720
	ds_write_b16 v197, v123 offset:864
	ds_write_b16_d16_hi v197, v123 offset:1008
	ds_write_b128 v196, v[88:91] offset:36864
	s_waitcnt vmcnt(9)
	ds_write_b16 v195, v112
	ds_write_b16_d16_hi v195, v112 offset:144
	ds_write_b16 v195, v113 offset:288
	ds_write_b16_d16_hi v195, v113 offset:432
	ds_write_b16 v195, v114 offset:576
	ds_write_b16_d16_hi v195, v114 offset:720
	ds_write_b16 v195, v115 offset:864
	ds_write_b16_d16_hi v195, v115 offset:1008
	ds_write_b128 v194, v[80:83] offset:36864
	s_waitcnt vmcnt(8)
	ds_write_b16 v193, v96
	ds_write_b16_d16_hi v193, v96 offset:144
	ds_write_b16 v193, v97 offset:288
	ds_write_b16_d16_hi v193, v97 offset:432
	ds_write_b16 v193, v98 offset:576
	ds_write_b16_d16_hi v193, v98 offset:720
	ds_write_b16 v193, v99 offset:864
	ds_write_b16_d16_hi v193, v99 offset:1008
	ds_write_b128 v2, v[72:75] offset:36864
	s_waitcnt lgkmcnt(0)
	s_barrier
	ds_read_b128 v[72:75], v201
	ds_read_b128 v[80:83], v201 offset:32
	ds_read_b128 v[88:91], v201 offset:4608
	ds_read_b128 v[96:99], v201 offset:4640
	ds_read_b128 v[104:107], v200 offset:36864
	ds_read_b128 v[112:115], v200 offset:36896
	ds_read_b128 v[120:123], v200 offset:41472
	ds_read_b128 v[128:131], v200 offset:41504
	s_waitcnt lgkmcnt(3)
	v_mfma_f32_32x32x16_bf16 v[52:67], v[72:75], v[104:107], v[52:67]
	s_waitcnt lgkmcnt(1)
	v_mfma_f32_32x32x16_bf16 v[36:51], v[72:75], v[120:123], v[36:51]
	v_mfma_f32_32x32x16_bf16 v[4:19], v[88:91], v[120:123], v[4:19]
	s_waitcnt lgkmcnt(0)
	v_mfma_f32_32x32x16_bf16 v[36:51], v[80:83], v[128:131], v[36:51]
	v_mfma_f32_32x32x16_bf16 v[4:19], v[96:99], v[128:131], v[4:19]
	ds_read_b128 v[128:131], v200 offset:41568
	ds_read_b128 v[72:75], v201 offset:4672
	v_mfma_f32_32x32x16_bf16 v[20:35], v[88:91], v[104:107], v[20:35]
	ds_read_b128 v[104:107], v201 offset:4704
	ds_read_b128 v[88:91], v201 offset:64
	v_mfma_f32_32x32x16_bf16 v[52:67], v[80:83], v[112:115], v[52:67]
	ds_read_b128 v[120:123], v200 offset:36960
	ds_read_b128 v[80:83], v200 offset:41536
	v_mfma_f32_32x32x16_bf16 v[20:35], v[96:99], v[112:115], v[20:35]
	ds_read_b128 v[112:115], v200 offset:36928
	ds_read_b128 v[96:99], v201 offset:96
	s_waitcnt lgkmcnt(1)
	v_mfma_f32_32x32x16_bf16 v[52:67], v[88:91], v[112:115], v[52:67]
	s_waitcnt vmcnt(3)
	ds_write_b16 v199, v124 offset:18432
	v_mfma_f32_32x32x16_bf16 v[36:51], v[88:91], v[80:83], v[36:51]
	ds_write_b16_d16_hi v199, v124 offset:18576
	v_mfma_f32_32x32x16_bf16 v[20:35], v[72:75], v[112:115], v[20:35]
	ds_write_b16 v199, v125 offset:18720
	v_mfma_f32_32x32x16_bf16 v[4:19], v[72:75], v[80:83], v[4:19]
	ds_write_b16_d16_hi v199, v125 offset:18864
	s_waitcnt lgkmcnt(4)
; #define MFMA(a, b, c) __builtin_amdgcn_mfma_f32_32x32x16_bf16((a), (b), (c), 0, 0, 0)
; DI int crow(int reg, int h) { return (reg & 3) + 8 * (reg >> 2) + 4 * h; }
; template <class Epi, class ColV>
; DI void gemm_tile(const bf16_t* __restrict__ A, int lda, const bf16_t* __restrict__ Bt, int ldb, int K, int m0, int n0, unsigned char* smem, Epi epi, ColV colv, const bf16_t* __restrict__ HYT = nullptr) {
;     ...
;         for (int k2 = 0; k2 < 2; ++k2) {
;             acc[0][0] = MFMA(ga[k2][0], gb[k2][0], acc[0][0]); acc[0][1] = MFMA(ga[k2][0], gb[k2][1], acc[0][1]);
;             acc[1][0] = MFMA(ga[k2][1], gb[k2][0], acc[1][0]); acc[1][1] = MFMA(ga[k2][1], gb[k2][1], acc[1][1]);
;         }
;         if (kt + 1 < nk) sstore(stset, buf ^ 1, kt + 1);
; #pragma unroll
;         for (int i = 0; i < 8; ++i) { __builtin_amdgcn_sched_group_barrier(0x008, 1, 0); __builtin_amdgcn_sched_group_barrier(0x100, 1, 0); }
; #pragma unroll
;         for (int i = 0; i < 8; ++i) { __builtin_amdgcn_sched_group_barrier(0x008, 1, 0); __builtin_amdgcn_sched_group_barrier(0x200, 1, 0); }
;         __builtin_amdgcn_sched_barrier(0);
;         __syncthreads();
;     };
;     gload(R0, 0); gload(R1, 1);
;     sstore(R0, 0, 0); __syncthreads();
;     for (int kt = 0; kt < nk; kt += 2) {
;         step(kt, R0, R1);
;         if (kt + 1 < nk) step(kt + 1, R1, R0);
;     }
;     const float cv0 = colv(m0, n0 + 64 * wc + li), cv1 = colv(m0, n0 + 64 * wc + 32 + li);
; #pragma unroll
;     for (int mi = 0; mi < 2; ++mi)
; #pragma unroll
;         for (int ni = 0; ni < 2; ++ni)
; #pragma unroll
;             for (int reg = 0; reg < 16; ++reg)
;                 epi(m0 + 64 * wr + 32 * mi + crow(reg, lh), n0 + 64 * wc + 32 * ni + li, acc[mi][ni][reg], ni ? cv1 : cv0);
;     ...
;         auto gate = [&](int m0_, int c) { return MOD[(m0_ < NL ? (m0_ >> 12) : 4) * 6144 + 2048 + c]; };
;         auto epi = [&](int r, int c, float v, float ga) {
;             if (r < NL) { const size_t o = (size_t)r * 1024 + c; out[o] = (layer == 0 ? xin[o] : out[o]) + ga * v; }
;             else { const size_t o = (size_t)(r - NL) * 1024 + c; XC[o] = cin[o] + ga * v; } };
;         XCD_TILE_LOOP((layer == 0 ? NT : NL) / 128, 8, tm, tn) gemm_tile((const bf16_t*)(p.ws + WS_MIX), 1024, (const bf16_t*)(p.ws + wbase(layer) + W_OUT), 1024, 1024, tm * 128, tn * 128, smem, epi, gate, (const bf16_t*)(p.ws + WS_HYOT));
	v_mfma_f32_32x32x16_bf16 v[52:67], v[96:99], v[120:123], v[52:67]
	ds_write_b16 v199, v126 offset:19008
	v_mfma_f32_32x32x16_bf16 v[36:51], v[96:99], v[128:131], v[36:51]
	ds_write_b16_d16_hi v199, v126 offset:19152
	v_mfma_f32_32x32x16_bf16 v[20:35], v[104:107], v[120:123], v[20:35]
	ds_write_b16 v199, v127 offset:19296
	v_mfma_f32_32x32x16_bf16 v[4:19], v[104:107], v[128:131], v[4:19]
	ds_write_b16_d16_hi v199, v127 offset:19440
	ds_write_b128 v198, v[100:103] offset:55296
	s_waitcnt vmcnt(2)
	ds_write_b16 v197, v116 offset:18432
	ds_write_b16_d16_hi v197, v116 offset:18576
	ds_write_b16 v197, v117 offset:18720
	ds_write_b16_d16_hi v197, v117 offset:18864
	ds_write_b16 v197, v118 offset:19008
	ds_write_b16_d16_hi v197, v118 offset:19152
	ds_write_b16 v197, v119 offset:19296
	ds_write_b16_d16_hi v197, v119 offset:19440
	ds_write_b128 v196, v[84:87] offset:55296
	s_waitcnt vmcnt(1)
	ds_write_b16 v195, v108 offset:18432
	ds_write_b16_d16_hi v195, v108 offset:18576
	ds_write_b16 v195, v109 offset:18720
	ds_write_b16_d16_hi v195, v109 offset:18864
	ds_write_b16 v195, v110 offset:19008
	ds_write_b16_d16_hi v195, v110 offset:19152
	ds_write_b16 v195, v111 offset:19296
	ds_write_b16_d16_hi v195, v111 offset:19440
	ds_write_b128 v194, v[76:79] offset:55296
	s_waitcnt vmcnt(0)
	ds_write_b16 v193, v92 offset:18432
	ds_write_b16_d16_hi v193, v92 offset:18576
	ds_write_b16 v193, v93 offset:18720
	ds_write_b16_d16_hi v193, v93 offset:18864
	ds_write_b16 v193, v94 offset:19008
	ds_write_b16_d16_hi v193, v94 offset:19152
	ds_write_b16 v193, v95 offset:19296
	ds_write_b16_d16_hi v193, v95 offset:19440
	ds_write_b128 v2, v[68:71] offset:55296
	s_waitcnt lgkmcnt(0)
	s_barrier
	ds_read_b128 v[68:71], v192
	ds_read_b128 v[72:75], v192 offset:32
	ds_read_b128 v[76:79], v192 offset:4608
	ds_read_b128 v[80:83], v192 offset:4640
	ds_read_b128 v[84:87], v191 offset:36864
	ds_read_b128 v[88:91], v191 offset:36896
	ds_read_b128 v[92:95], v191 offset:41472
	ds_read_b128 v[96:99], v191 offset:41504
	s_waitcnt lgkmcnt(3)
	v_mfma_f32_32x32x16_bf16 v[52:67], v[68:71], v[84:87], v[52:67]
	s_waitcnt lgkmcnt(1)
	v_mfma_f32_32x32x16_bf16 v[36:51], v[68:71], v[92:95], v[36:51]
	v_mfma_f32_32x32x16_bf16 v[4:19], v[76:79], v[92:95], v[4:19]
	s_waitcnt lgkmcnt(0)
	v_mfma_f32_32x32x16_bf16 v[36:51], v[72:75], v[96:99], v[36:51]
	v_mfma_f32_32x32x16_bf16 v[4:19], v[80:83], v[96:99], v[4:19]
	ds_read_b128 v[96:99], v191 offset:41568
	ds_read_b128 v[68:71], v192 offset:4672
	v_mfma_f32_32x32x16_bf16 v[20:35], v[76:79], v[84:87], v[20:35]
	ds_read_b128 v[84:87], v192 offset:4704
	ds_read_b128 v[76:79], v192 offset:64
	v_mfma_f32_32x32x16_bf16 v[52:67], v[72:75], v[88:91], v[52:67]
	ds_read_b128 v[92:95], v191 offset:36960
	ds_read_b128 v[72:75], v191 offset:41536
	v_mfma_f32_32x32x16_bf16 v[20:35], v[80:83], v[88:91], v[20:35]
	ds_read_b128 v[88:91], v191 offset:36928
	ds_read_b128 v[80:83], v192 offset:96
	s_waitcnt lgkmcnt(1)
	v_mfma_f32_32x32x16_bf16 v[52:67], v[76:79], v[88:91], v[52:67]
	v_mfma_f32_32x32x16_bf16 v[36:51], v[76:79], v[72:75], v[36:51]
	v_mfma_f32_32x32x16_bf16 v[20:35], v[68:71], v[88:91], v[20:35]
	v_mfma_f32_32x32x16_bf16 v[4:19], v[68:71], v[72:75], v[4:19]
	s_waitcnt lgkmcnt(0)
	v_mfma_f32_32x32x16_bf16 v[52:67], v[80:83], v[92:95], v[52:67]
	v_mfma_f32_32x32x16_bf16 v[36:51], v[80:83], v[96:99], v[36:51]
	v_mfma_f32_32x32x16_bf16 v[20:35], v[84:87], v[92:95], v[20:35]
	v_mfma_f32_32x32x16_bf16 v[4:19], v[84:87], v[96:99], v[4:19]
	s_min_i32 s13, s12, 0x4000
	s_ashr_i32 s13, s13, 12
	s_mulk_i32 s13, 0x1800
	v_bitop3_b32 v68, v151, 31, 64 bitop3:0xe0
	v_or_b32_e32 v0, s13, v68
	v_subrev_u32_e32 v0, s38, v0
	v_add_u32_e32 v2, s36, v0
	v_add_u32_e32 v0, 0x800, v2
	v_ashrrev_i32_e32 v1, 31, v0
	v_lshl_add_u64 v[0:1], v[0:1], 2, s[46:47]
	s_barrier
	global_load_dword v108, v[0:1], off
	v_add_u32_e32 v0, 0x820, v2
	v_ashrrev_i32_e32 v1, 31, v0
	v_lshl_add_u64 v[0:1], v[0:1], 2, s[46:47]
	global_load_dword v2, v[0:1], off
	v_add_u32_e32 v0, s12, v190
	v_lshl_or_b32 v109, v148, 2, v0
	v_subrev_u32_e32 v0, s38, v68
	v_add_u32_e32 v0, s36, v0
	s_cmp_lt_i32 s12, 0x4000
	s_cselect_b32 s100, s15, s48
	s_cselect_b32 s101, s9, s49
	s_cselect_b32 s13, 0, 0x4000
	v_subrev_u32_e32 v109, s13, v109
	v_lshlrev_b32_e32 v109, 12, v109
	v_lshl_add_u32 v109, v0, 2, v109
	s_cselect_b32 s12, s24, s96
	s_cselect_b32 s13, s25, s97
	v_mov_b32_e32 v0, v109
	global_load_dword v69, v0, s[100:101]
	global_load_dword v70, v0, s[100:101] offset:128
	v_add_u32_e32 v0, 0x1000, v0
	global_load_dword v71, v0, s[100:101]
	global_load_dword v72, v0, s[100:101] offset:128
	v_add_u32_e32 v0, 0x1000, v0
	global_load_dword v73, v0, s[100:101]
	global_load_dword v74, v0, s[100:101] offset:128
	v_add_u32_e32 v0, 0x1000, v0
	global_load_dword v75, v0, s[100:101]
	global_load_dword v76, v0, s[100:101] offset:128
	v_add_u32_e32 v0, 0x5000, v0
	global_load_dword v77, v0, s[100:101]
	global_load_dword v78, v0, s[100:101] offset:128
	v_add_u32_e32 v0, 0x1000, v0
	global_load_dword v79, v0, s[100:101]
	global_load_dword v80, v0, s[100:101] offset:128
	v_add_u32_e32 v0, 0x1000, v0
	global_load_dword v81, v0, s[100:101]
	global_load_dword v82, v0, s[100:101] offset:128
	v_add_u32_e32 v0, 0x1000, v0
	global_load_dword v83, v0, s[100:101]
	global_load_dword v84, v0, s[100:101] offset:128
	v_add_u32_e32 v0, 0x5000, v0
	global_load_dword v85, v0, s[100:101]
	global_load_dword v86, v0, s[100:101] offset:128
	v_add_u32_e32 v0, 0x1000, v0
	global_load_dword v87, v0, s[100:101]
	global_load_dword v88, v0, s[100:101] offset:128
	v_add_u32_e32 v0, 0x1000, v0
	global_load_dword v89, v0, s[100:101]
	global_load_dword v90, v0, s[100:101] offset:128
	v_add_u32_e32 v0, 0x1000, v0
	global_load_dword v91, v0, s[100:101]
	global_load_dword v92, v0, s[100:101] offset:128
	v_add_u32_e32 v0, 0x5000, v0
	global_load_dword v93, v0, s[100:101]
	global_load_dword v94, v0, s[100:101] offset:128
	v_add_u32_e32 v0, 0x1000, v0
	global_load_dword v95, v0, s[100:101]
	global_load_dword v96, v0, s[100:101] offset:128
	v_add_u32_e32 v0, 0x1000, v0
	global_load_dword v97, v0, s[100:101]
	global_load_dword v98, v0, s[100:101] offset:128
	v_add_u32_e32 v0, 0x1000, v0
	global_load_dword v99, v0, s[100:101]
	global_load_dword v100, v0, s[100:101] offset:128
	s_waitcnt vmcnt(0)
; DI int crow(int reg, int h) { return (reg & 3) + 8 * (reg >> 2) + 4 * h; }
; template <class Epi, class ColV>
; DI void gemm_tile(const bf16_t* __restrict__ A, int lda, const bf16_t* __restrict__ Bt, int ldb, int K, int m0, int n0, unsigned char* smem, Epi epi, ColV colv, const bf16_t* __restrict__ HYT = nullptr) {
;     ...
;     const float cv0 = colv(m0, n0 + 64 * wc + li), cv1 = colv(m0, n0 + 64 * wc + 32 + li);
; #pragma unroll
;     for (int mi = 0; mi < 2; ++mi)
; #pragma unroll
;         for (int ni = 0; ni < 2; ++ni)
; #pragma unroll
;             for (int reg = 0; reg < 16; ++reg)
;                 epi(m0 + 64 * wr + 32 * mi + crow(reg, lh), n0 + 64 * wc + 32 * ni + li, acc[mi][ni][reg], ni ? cv1 : cv0);
;     ...
;         auto epi = [&](int r, int c, float v, float ga) {
;             if (r < NL) { const size_t o = (size_t)r * 1024 + c; out[o] = (layer == 0 ? xin[o] : out[o]) + ga * v; }
;             else { const size_t o = (size_t)(r - NL) * 1024 + c; XC[o] = cin[o] + ga * v; } };
	v_fmac_f32_e32 v69, v52, v108
	v_fmac_f32_e32 v70, v36, v2
	v_fmac_f32_e32 v71, v53, v108
	v_fmac_f32_e32 v72, v37, v2
	v_fmac_f32_e32 v73, v54, v108
	v_fmac_f32_e32 v74, v38, v2
	v_fmac_f32_e32 v75, v55, v108
	v_fmac_f32_e32 v76, v39, v2
	v_fmac_f32_e32 v77, v56, v108
	v_fmac_f32_e32 v78, v40, v2
	v_fmac_f32_e32 v79, v57, v108
	v_fmac_f32_e32 v80, v41, v2
	v_fmac_f32_e32 v81, v58, v108
	v_fmac_f32_e32 v82, v42, v2
	v_fmac_f32_e32 v83, v59, v108
	v_fmac_f32_e32 v84, v43, v2
	v_fmac_f32_e32 v85, v60, v108
	v_fmac_f32_e32 v86, v44, v2
	v_fmac_f32_e32 v87, v61, v108
	v_fmac_f32_e32 v88, v45, v2
	v_fmac_f32_e32 v89, v62, v108
	v_fmac_f32_e32 v90, v46, v2
	v_fmac_f32_e32 v91, v63, v108
	v_fmac_f32_e32 v92, v47, v2
	v_fmac_f32_e32 v93, v64, v108
	v_fmac_f32_e32 v94, v48, v2
	v_fmac_f32_e32 v95, v65, v108
	v_fmac_f32_e32 v96, v49, v2
	v_fmac_f32_e32 v97, v66, v108
	v_fmac_f32_e32 v98, v50, v2
	v_fmac_f32_e32 v99, v67, v108
	v_fmac_f32_e32 v100, v51, v2
	v_mov_b32_e32 v0, v109
	global_store_dword v0, v69, s[12:13]
	global_store_dword v0, v70, s[12:13] offset:128
	v_add_u32_e32 v0, 0x1000, v0
	global_store_dword v0, v71, s[12:13]
	global_store_dword v0, v72, s[12:13] offset:128
	v_add_u32_e32 v0, 0x1000, v0
	global_store_dword v0, v73, s[12:13]
	global_store_dword v0, v74, s[12:13] offset:128
	v_add_u32_e32 v0, 0x1000, v0
	global_store_dword v0, v75, s[12:13]
	global_store_dword v0, v76, s[12:13] offset:128
	v_add_u32_e32 v0, 0x5000, v0
	global_store_dword v0, v77, s[12:13]
	global_store_dword v0, v78, s[12:13] offset:128
	v_add_u32_e32 v0, 0x1000, v0
	global_store_dword v0, v79, s[12:13]
	global_store_dword v0, v80, s[12:13] offset:128
	v_add_u32_e32 v0, 0x1000, v0
	global_store_dword v0, v81, s[12:13]
	global_store_dword v0, v82, s[12:13] offset:128
	v_add_u32_e32 v0, 0x1000, v0
	global_store_dword v0, v83, s[12:13]
	global_store_dword v0, v84, s[12:13] offset:128
	v_add_u32_e32 v0, 0x5000, v0
	global_store_dword v0, v85, s[12:13]
	global_store_dword v0, v86, s[12:13] offset:128
	v_add_u32_e32 v0, 0x1000, v0
	global_store_dword v0, v87, s[12:13]
	global_store_dword v0, v88, s[12:13] offset:128
	v_add_u32_e32 v0, 0x1000, v0
	global_store_dword v0, v89, s[12:13]
	global_store_dword v0, v90, s[12:13] offset:128
	v_add_u32_e32 v0, 0x1000, v0
	global_store_dword v0, v91, s[12:13]
	global_store_dword v0, v92, s[12:13] offset:128
	v_add_u32_e32 v0, 0x5000, v0
	global_store_dword v0, v93, s[12:13]
	global_store_dword v0, v94, s[12:13] offset:128
	v_add_u32_e32 v0, 0x1000, v0
	global_store_dword v0, v95, s[12:13]
	global_store_dword v0, v96, s[12:13] offset:128
	v_add_u32_e32 v0, 0x1000, v0
	global_store_dword v0, v97, s[12:13]
	global_store_dword v0, v98, s[12:13] offset:128
	v_add_u32_e32 v0, 0x1000, v0
	global_store_dword v0, v99, s[12:13]
	global_store_dword v0, v100, s[12:13] offset:128
	v_add_u32_e32 v0, 0x20000, v109
	global_load_dword v101, v0, s[100:101]
	global_load_dword v102, v0, s[100:101] offset:128
	v_add_u32_e32 v0, 0x1000, v0
	global_load_dword v103, v0, s[100:101]
	global_load_dword v104, v0, s[100:101] offset:128
	v_add_u32_e32 v0, 0x1000, v0
	global_load_dword v105, v0, s[100:101]
	global_load_dword v106, v0, s[100:101] offset:128
	v_add_u32_e32 v0, 0x1000, v0
	global_load_dword v107, v0, s[100:101]
	global_load_dword v110, v0, s[100:101] offset:128
	v_add_u32_e32 v0, 0x5000, v0
	global_load_dword v111, v0, s[100:101]
	global_load_dword v112, v0, s[100:101] offset:128
	v_add_u32_e32 v0, 0x1000, v0
	global_load_dword v113, v0, s[100:101]
	global_load_dword v114, v0, s[100:101] offset:128
	v_add_u32_e32 v0, 0x1000, v0
	global_load_dword v115, v0, s[100:101]
	global_load_dword v116, v0, s[100:101] offset:128
	v_add_u32_e32 v0, 0x1000, v0
	global_load_dword v117, v0, s[100:101]
	global_load_dword v118, v0, s[100:101] offset:128
	v_add_u32_e32 v0, 0x5000, v0
	global_load_dword v119, v0, s[100:101]
	global_load_dword v120, v0, s[100:101] offset:128
	v_add_u32_e32 v0, 0x1000, v0
	global_load_dword v121, v0, s[100:101]
	global_load_dword v122, v0, s[100:101] offset:128
	v_add_u32_e32 v0, 0x1000, v0
	global_load_dword v123, v0, s[100:101]
	global_load_dword v124, v0, s[100:101] offset:128
	v_add_u32_e32 v0, 0x1000, v0
	global_load_dword v125, v0, s[100:101]
	global_load_dword v126, v0, s[100:101] offset:128
	v_add_u32_e32 v0, 0x5000, v0
	global_load_dword v127, v0, s[100:101]
	global_load_dword v128, v0, s[100:101] offset:128
	v_add_u32_e32 v0, 0x1000, v0
	global_load_dword v129, v0, s[100:101]
	global_load_dword v130, v0, s[100:101] offset:128
	v_add_u32_e32 v0, 0x1000, v0
	global_load_dword v131, v0, s[100:101]
	global_load_dword v132, v0, s[100:101] offset:128
	v_add_u32_e32 v0, 0x1000, v0
	global_load_dword v133, v0, s[100:101]
	global_load_dword v134, v0, s[100:101] offset:128
	s_waitcnt vmcnt(0)
; DI int crow(int reg, int h) { return (reg & 3) + 8 * (reg >> 2) + 4 * h; }
; template <class Epi, class ColV>
; DI void gemm_tile(const bf16_t* __restrict__ A, int lda, const bf16_t* __restrict__ Bt, int ldb, int K, int m0, int n0, unsigned char* smem, Epi epi, ColV colv, const bf16_t* __restrict__ HYT = nullptr) {
;     ...
;     const float cv0 = colv(m0, n0 + 64 * wc + li), cv1 = colv(m0, n0 + 64 * wc + 32 + li);
; #pragma unroll
;     for (int mi = 0; mi < 2; ++mi)
; #pragma unroll
;         for (int ni = 0; ni < 2; ++ni)
; #pragma unroll
;             for (int reg = 0; reg < 16; ++reg)
;                 epi(m0 + 64 * wr + 32 * mi + crow(reg, lh), n0 + 64 * wc + 32 * ni + li, acc[mi][ni][reg], ni ? cv1 : cv0);
;     ...
;         auto epi = [&](int r, int c, float v, float ga) {
;             if (r < NL) { const size_t o = (size_t)r * 1024 + c; out[o] = (layer == 0 ? xin[o] : out[o]) + ga * v; }
;             else { const size_t o = (size_t)(r - NL) * 1024 + c; XC[o] = cin[o] + ga * v; } };
	v_fmac_f32_e32 v101, v20, v108
	v_fmac_f32_e32 v102, v4, v2
	v_fmac_f32_e32 v103, v21, v108
	v_fmac_f32_e32 v104, v5, v2
	v_fmac_f32_e32 v105, v22, v108
	v_fmac_f32_e32 v106, v6, v2
	v_fmac_f32_e32 v107, v23, v108
	v_fmac_f32_e32 v110, v7, v2
	v_fmac_f32_e32 v111, v24, v108
	v_fmac_f32_e32 v112, v8, v2
	v_fmac_f32_e32 v113, v25, v108
	v_fmac_f32_e32 v114, v9, v2
	v_fmac_f32_e32 v115, v26, v108
	v_fmac_f32_e32 v116, v10, v2
	v_fmac_f32_e32 v117, v27, v108
	v_fmac_f32_e32 v118, v11, v2
	v_fmac_f32_e32 v119, v28, v108
	v_fmac_f32_e32 v120, v12, v2
	v_fmac_f32_e32 v121, v29, v108
	v_fmac_f32_e32 v122, v13, v2
	v_fmac_f32_e32 v123, v30, v108
	v_fmac_f32_e32 v124, v14, v2
	v_fmac_f32_e32 v125, v31, v108
	v_fmac_f32_e32 v126, v15, v2
	v_fmac_f32_e32 v127, v32, v108
	v_fmac_f32_e32 v128, v16, v2
	v_fmac_f32_e32 v129, v33, v108
	v_fmac_f32_e32 v130, v17, v2
	v_fmac_f32_e32 v131, v34, v108
	v_fmac_f32_e32 v132, v18, v2
	v_fmac_f32_e32 v133, v35, v108
	v_fmac_f32_e32 v134, v19, v2
	v_add_u32_e32 v0, 0x20000, v109
	global_store_dword v0, v101, s[12:13]
	global_store_dword v0, v102, s[12:13] offset:128
	v_add_u32_e32 v0, 0x1000, v0
	global_store_dword v0, v103, s[12:13]
	global_store_dword v0, v104, s[12:13] offset:128
	v_add_u32_e32 v0, 0x1000, v0
	global_store_dword v0, v105, s[12:13]
	global_store_dword v0, v106, s[12:13] offset:128
	v_add_u32_e32 v0, 0x1000, v0
	global_store_dword v0, v107, s[12:13]
	global_store_dword v0, v110, s[12:13] offset:128
	v_add_u32_e32 v0, 0x5000, v0
	global_store_dword v0, v111, s[12:13]
	global_store_dword v0, v112, s[12:13] offset:128
	v_add_u32_e32 v0, 0x1000, v0
	global_store_dword v0, v113, s[12:13]
	global_store_dword v0, v114, s[12:13] offset:128
	v_add_u32_e32 v0, 0x1000, v0
	global_store_dword v0, v115, s[12:13]
	global_store_dword v0, v116, s[12:13] offset:128
	v_add_u32_e32 v0, 0x1000, v0
	global_store_dword v0, v117, s[12:13]
	global_store_dword v0, v118, s[12:13] offset:128
	v_add_u32_e32 v0, 0x5000, v0
	global_store_dword v0, v119, s[12:13]
	global_store_dword v0, v120, s[12:13] offset:128
	v_add_u32_e32 v0, 0x1000, v0
	global_store_dword v0, v121, s[12:13]
	global_store_dword v0, v122, s[12:13] offset:128
	v_add_u32_e32 v0, 0x1000, v0
	global_store_dword v0, v123, s[12:13]
	global_store_dword v0, v124, s[12:13] offset:128
	v_add_u32_e32 v0, 0x1000, v0
	global_store_dword v0, v125, s[12:13]
	global_store_dword v0, v126, s[12:13] offset:128
	v_add_u32_e32 v0, 0x5000, v0
	global_store_dword v0, v127, s[12:13]
	global_store_dword v0, v128, s[12:13] offset:128
	v_add_u32_e32 v0, 0x1000, v0
	global_store_dword v0, v129, s[12:13]
	global_store_dword v0, v130, s[12:13] offset:128
	v_add_u32_e32 v0, 0x1000, v0
	global_store_dword v0, v131, s[12:13]
	global_store_dword v0, v132, s[12:13] offset:128
	v_add_u32_e32 v0, 0x1000, v0
	global_store_dword v0, v133, s[12:13]
	global_store_dword v0, v134, s[12:13] offset:128
	s_add_i32 s37, s37, s18
	s_add_i32 s36, s36, s19
	s_cmp_lt_i32 s37, s8
	s_cbranch_scc1 .LBB0_79
